# lane-transposed (ds_bpermute) f32 epilogue stores for kinds 16, 17-19, 14, 12: consecutive lanes write consecutive addresses instead of consecutive rows; on top of v34
# speedup vs baseline: 1.0121x; 1.0121x over previous
; __device__ __forceinline__ void epilogue(const Params& p, const Unit& u, const f32x4 (&acc)[2][2][4][2], int wr, int wc, int fr, int fq) {
;     ...
;   } else {
;     const float* x1 = (const float*)(ws + WS_X1);
;     float* yo = (float*)(ws + WS_YPRE);
;     const int cb = u.pn * 256 + ct0;
; #pragma unroll
;     for (int ai = 0; ai < 2; ++ai)
; #pragma unroll
;       for (int mp = 0; mp < 2; ++mp) {
;         f32x4 xv[2][2][2];
; #pragma unroll
;         for (int mm = 0; mm < 2; ++mm) {
;           const size_t row = (size_t)(row0 + ai * 128 + (mp * 2 + mm) * 16);
; #pragma unroll
;           for (int bj = 0; bj < 2; ++bj)
; #pragma unroll
;             for (int n = 0; n < 2; ++n) xv[mm][bj][n] = *(const f32x4*)(x1 + row * 2048 + cb + bj * 128 + n * 16);
;         }
; #pragma unroll
;         for (int mm = 0; mm < 2; ++mm) {
;           const size_t row = (size_t)(row0 + ai * 128 + (mp * 2 + mm) * 16);
; #pragma unroll
;           for (int bj = 0; bj < 2; ++bj)
; #pragma unroll
;             for (int n = 0; n < 2; ++n) *(f32x4*)(yo + row * 2048 + cb + bj * 128 + n * 16) = xv[mm][bj][n] * ALPHA + acc[ai][bj][mp * 2 + mm][n];
;         }
;       }
;   }
.LBB0_357:
	s_cmp_lt_u32 s76, 17
	s_mov_b64 s[36:37], -1
	s_cbranch_scc0 .Le3_ep
	s_cmp_lg_u32 s76, 16
	s_cbranch_scc0 .LBB0_360
	s_branch .Le14_ep
	v_lshl_or_b32 v132, s78, 8, v174
	v_ashrrev_i32_e32 v133, 31, v132
	v_readlane_b32 s34, v254, 30
	v_lshlrev_b64 v[134:135], 2, v[132:133]
	v_readlane_b32 s35, v254, 31
	v_ashrrev_i32_e32 v67, 31, v66
	v_or_b32_e32 v152, 16, v66
	v_lshl_add_u64 v[132:133], s[34:35], 0, v[134:135]
	v_readlane_b32 s34, v252, 57
	v_readlane_b32 s35, v252, 58
	v_ashrrev_i32_e32 v153, 31, v152
	v_lshlrev_b64 v[166:167], 13, v[152:153]
	v_lshl_add_u64 v[164:165], s[34:35], 0, v[134:135]
	v_lshlrev_b64 v[134:135], 13, v[66:67]
	v_lshl_add_u64 v[148:149], v[132:133], 0, v[134:135]
	global_load_dwordx4 v[136:139], v[148:149], off
	global_load_dwordx4 v[140:143], v[148:149], off offset:64
	global_load_dwordx4 v[144:147], v[148:149], off offset:512
	s_nop 0
	global_load_dwordx4 v[148:151], v[148:149], off offset:576
	v_lshl_add_u64 v[196:197], v[132:133], 0, v[166:167]
	global_load_dwordx4 v[152:155], v[196:197], off
	global_load_dwordx4 v[156:159], v[196:197], off offset:64
	global_load_dwordx4 v[160:163], v[196:197], off offset:512
	s_nop 0
	global_load_dwordx4 v[196:199], v[196:197], off offset:576
	v_lshl_add_u64 v[200:201], v[164:165], 0, v[134:135]
	s_mov_b64 s[34:35], 0x100000
	s_mov_b64 s[36:37], 0x140000
	s_waitcnt vmcnt(0)
	v_pk_fma_f32 v[138:139], v[138:139], s[2:3], v[130:131] op_sel_hi:[1,0,1]
	v_pk_fma_f32 v[136:137], v[136:137], s[2:3], v[128:129] op_sel_hi:[1,0,1]
	global_store_dwordx4 v[200:201], v[136:139], off
	s_nop 1
	v_pk_fma_f32 v[138:139], v[142:143], s[2:3], v[126:127] op_sel_hi:[1,0,1]
	v_pk_fma_f32 v[136:137], v[140:141], s[2:3], v[124:125] op_sel_hi:[1,0,1]
	global_store_dwordx4 v[200:201], v[136:139], off offset:64
	v_lshl_add_u64 v[140:141], v[164:165], 0, v[166:167]
	s_nop 0
	v_pk_fma_f32 v[138:139], v[146:147], s[2:3], v[98:99] op_sel_hi:[1,0,1]
	v_pk_fma_f32 v[136:137], v[144:145], s[2:3], v[96:97] op_sel_hi:[1,0,1]
	global_store_dwordx4 v[200:201], v[136:139], off offset:512
	s_nop 1
	v_pk_fma_f32 v[138:139], v[150:151], s[2:3], v[94:95] op_sel_hi:[1,0,1]
	v_pk_fma_f32 v[136:137], v[148:149], s[2:3], v[92:93] op_sel_hi:[1,0,1]
	global_store_dwordx4 v[200:201], v[136:139], off offset:576
	s_nop 1
	v_pk_fma_f32 v[138:139], v[154:155], s[2:3], v[122:123] op_sel_hi:[1,0,1]
	v_pk_fma_f32 v[136:137], v[152:153], s[2:3], v[120:121] op_sel_hi:[1,0,1]
	global_store_dwordx4 v[140:141], v[136:139], off
	v_or_b32_e32 v152, 48, v66
	v_ashrrev_i32_e32 v153, 31, v152
	v_pk_fma_f32 v[138:139], v[158:159], s[2:3], v[118:119] op_sel_hi:[1,0,1]
	v_pk_fma_f32 v[136:137], v[156:157], s[2:3], v[116:117] op_sel_hi:[1,0,1]
	global_store_dwordx4 v[140:141], v[136:139], off offset:64
	v_lshlrev_b64 v[200:201], 13, v[152:153]
	s_nop 0
	v_pk_fma_f32 v[138:139], v[162:163], s[2:3], v[90:91] op_sel_hi:[1,0,1]
	v_pk_fma_f32 v[136:137], v[160:161], s[2:3], v[88:89] op_sel_hi:[1,0,1]
	global_store_dwordx4 v[140:141], v[136:139], off offset:512
	s_nop 1
	v_pk_fma_f32 v[138:139], v[198:199], s[2:3], v[86:87] op_sel_hi:[1,0,1]
	v_pk_fma_f32 v[136:137], v[196:197], s[2:3], v[84:85] op_sel_hi:[1,0,1]
	global_store_dwordx4 v[140:141], v[136:139], off offset:576
	v_lshl_add_u64 v[196:197], v[132:133], 0, v[200:201]
	s_nop 0
	v_or_b32_e32 v136, 32, v66
	v_ashrrev_i32_e32 v137, 31, v136
	v_lshlrev_b64 v[166:167], 13, v[136:137]
	v_lshl_add_u64 v[148:149], v[132:133], 0, v[166:167]
	global_load_dwordx4 v[136:139], v[148:149], off
	global_load_dwordx4 v[140:143], v[148:149], off offset:64
	global_load_dwordx4 v[144:147], v[148:149], off offset:512
	s_nop 0
	global_load_dwordx4 v[148:151], v[148:149], off offset:576
	s_nop 0
	global_load_dwordx4 v[152:155], v[196:197], off
	global_load_dwordx4 v[156:159], v[196:197], off offset:64
	global_load_dwordx4 v[160:163], v[196:197], off offset:512
	s_nop 0
	global_load_dwordx4 v[196:199], v[196:197], off offset:576
	v_lshl_add_u64 v[166:167], v[164:165], 0, v[166:167]
	s_waitcnt vmcnt(0)
	v_pk_fma_f32 v[138:139], v[138:139], s[2:3], v[114:115] op_sel_hi:[1,0,1]
	v_pk_fma_f32 v[136:137], v[136:137], s[2:3], v[112:113] op_sel_hi:[1,0,1]
	global_store_dwordx4 v[166:167], v[136:139], off
	s_nop 1
	v_pk_fma_f32 v[138:139], v[142:143], s[2:3], v[110:111] op_sel_hi:[1,0,1]
	v_pk_fma_f32 v[136:137], v[140:141], s[2:3], v[108:109] op_sel_hi:[1,0,1]
	global_store_dwordx4 v[166:167], v[136:139], off offset:64
	v_lshl_add_u64 v[140:141], v[164:165], 0, v[200:201]
	s_nop 0
	v_pk_fma_f32 v[138:139], v[146:147], s[2:3], v[82:83] op_sel_hi:[1,0,1]
	v_pk_fma_f32 v[136:137], v[144:145], s[2:3], v[80:81] op_sel_hi:[1,0,1]
	global_store_dwordx4 v[166:167], v[136:139], off offset:512
	s_nop 1
	v_pk_fma_f32 v[138:139], v[150:151], s[2:3], v[78:79] op_sel_hi:[1,0,1]
	v_pk_fma_f32 v[136:137], v[148:149], s[2:3], v[76:77] op_sel_hi:[1,0,1]
	global_store_dwordx4 v[166:167], v[136:139], off offset:576
	v_lshl_add_u64 v[166:167], v[134:135], 0, s[34:35]
	v_lshl_add_u64 v[148:149], v[132:133], 0, v[166:167]
	v_pk_fma_f32 v[138:139], v[154:155], s[2:3], v[106:107] op_sel_hi:[1,0,1]
	v_pk_fma_f32 v[136:137], v[152:153], s[2:3], v[104:105] op_sel_hi:[1,0,1]
	global_store_dwordx4 v[140:141], v[136:139], off
	s_mov_b64 s[34:35], 0x120000
	v_lshl_add_u64 v[200:201], v[134:135], 0, s[34:35]
	v_pk_fma_f32 v[138:139], v[158:159], s[2:3], v[102:103] op_sel_hi:[1,0,1]
	v_pk_fma_f32 v[136:137], v[156:157], s[2:3], v[100:101] op_sel_hi:[1,0,1]
	global_store_dwordx4 v[140:141], v[136:139], off offset:64
	v_lshl_add_u64 v[166:167], v[164:165], 0, v[166:167]
	s_mov_b64 s[34:35], 0x160000
	v_pk_fma_f32 v[138:139], v[162:163], s[2:3], v[74:75] op_sel_hi:[1,0,1]
	v_pk_fma_f32 v[136:137], v[160:161], s[2:3], v[72:73] op_sel_hi:[1,0,1]
	global_store_dwordx4 v[140:141], v[136:139], off offset:512
	s_nop 1
	v_pk_fma_f32 v[138:139], v[198:199], s[2:3], v[70:71] op_sel_hi:[1,0,1]
	v_pk_fma_f32 v[136:137], v[196:197], s[2:3], v[68:69] op_sel_hi:[1,0,1]
	global_store_dwordx4 v[140:141], v[136:139], off offset:576
	global_load_dwordx4 v[136:139], v[148:149], off
	s_nop 0
	global_load_dwordx4 v[140:143], v[148:149], off offset:64
	global_load_dwordx4 v[144:147], v[148:149], off offset:512
	s_nop 0
	global_load_dwordx4 v[148:151], v[148:149], off offset:576
	v_lshl_add_u64 v[196:197], v[132:133], 0, v[200:201]
	global_load_dwordx4 v[152:155], v[196:197], off
	global_load_dwordx4 v[156:159], v[196:197], off offset:64
	global_load_dwordx4 v[160:163], v[196:197], off offset:512
	s_nop 0
	global_load_dwordx4 v[196:199], v[196:197], off offset:576
	s_waitcnt vmcnt(0)
; __device__ __forceinline__ void epilogue(const Params& p, const Unit& u, const f32x4 (&acc)[2][2][4][2], int wr, int wc, int fr, int fq) {
;     ...
;         f32x4 xv[2][2][2];
; #pragma unroll
;         for (int mm = 0; mm < 2; ++mm) {
;           const size_t row = (size_t)(row0 + ai * 128 + (mp * 2 + mm) * 16);
; #pragma unroll
;           for (int bj = 0; bj < 2; ++bj)
; #pragma unroll
;             for (int n = 0; n < 2; ++n) xv[mm][bj][n] = *(const f32x4*)(x1 + row * 2048 + cb + bj * 128 + n * 16);
;         }
; #pragma unroll
;         for (int mm = 0; mm < 2; ++mm) {
;           const size_t row = (size_t)(row0 + ai * 128 + (mp * 2 + mm) * 16);
; #pragma unroll
;           for (int bj = 0; bj < 2; ++bj)
; #pragma unroll
;             for (int n = 0; n < 2; ++n) *(f32x4*)(yo + row * 2048 + cb + bj * 128 + n * 16) = xv[mm][bj][n] * ALPHA + acc[ai][bj][mp * 2 + mm][n];
;         }
;       }
;   }
	v_pk_fma_f32 v[138:139], v[138:139], s[2:3], v[62:63] op_sel_hi:[1,0,1]
	v_pk_fma_f32 v[136:137], v[136:137], s[2:3], v[60:61] op_sel_hi:[1,0,1]
	global_store_dwordx4 v[166:167], v[136:139], off
	s_nop 1
	v_pk_fma_f32 v[138:139], v[142:143], s[2:3], v[58:59] op_sel_hi:[1,0,1]
	v_pk_fma_f32 v[136:137], v[140:141], s[2:3], v[56:57] op_sel_hi:[1,0,1]
	global_store_dwordx4 v[166:167], v[136:139], off offset:64
	v_lshl_add_u64 v[140:141], v[164:165], 0, v[200:201]
	s_nop 0
	v_pk_fma_f32 v[138:139], v[146:147], s[2:3], v[30:31] op_sel_hi:[1,0,1]
	v_pk_fma_f32 v[136:137], v[144:145], s[2:3], v[28:29] op_sel_hi:[1,0,1]
	global_store_dwordx4 v[166:167], v[136:139], off offset:512
	s_nop 1
	v_pk_fma_f32 v[138:139], v[150:151], s[2:3], v[26:27] op_sel_hi:[1,0,1]
	v_pk_fma_f32 v[136:137], v[148:149], s[2:3], v[24:25] op_sel_hi:[1,0,1]
	global_store_dwordx4 v[166:167], v[136:139], off offset:576
	v_lshl_add_u64 v[166:167], v[134:135], 0, s[36:37]
	s_mov_b64 s[36:37], 0
	v_pk_fma_f32 v[138:139], v[154:155], s[2:3], v[54:55] op_sel_hi:[1,0,1]
	v_pk_fma_f32 v[136:137], v[152:153], s[2:3], v[52:53] op_sel_hi:[1,0,1]
	global_store_dwordx4 v[140:141], v[136:139], off
	s_nop 1
	v_pk_fma_f32 v[138:139], v[158:159], s[2:3], v[50:51] op_sel_hi:[1,0,1]
	v_pk_fma_f32 v[136:137], v[156:157], s[2:3], v[48:49] op_sel_hi:[1,0,1]
	global_store_dwordx4 v[140:141], v[136:139], off offset:64
	s_nop 1
	v_pk_fma_f32 v[138:139], v[162:163], s[2:3], v[22:23] op_sel_hi:[1,0,1]
	v_pk_fma_f32 v[136:137], v[160:161], s[2:3], v[20:21] op_sel_hi:[1,0,1]
	global_store_dwordx4 v[140:141], v[136:139], off offset:512
	s_nop 1
	v_pk_fma_f32 v[138:139], v[198:199], s[2:3], v[18:19] op_sel_hi:[1,0,1]
	v_pk_fma_f32 v[136:137], v[196:197], s[2:3], v[16:17] op_sel_hi:[1,0,1]
	global_store_dwordx4 v[140:141], v[136:139], off offset:576
	v_lshl_add_u64 v[196:197], v[134:135], 0, s[34:35]
	s_nop 0
	v_lshl_add_u64 v[136:137], v[132:133], 0, v[166:167]
	global_load_dwordx4 v[160:163], v[136:137], off
	global_load_dwordx4 v[152:155], v[136:137], off offset:64
	global_load_dwordx4 v[156:159], v[136:137], off offset:512
	global_load_dwordx4 v[144:147], v[136:137], off offset:576
	v_lshl_add_u64 v[132:133], v[132:133], 0, v[196:197]
	global_load_dwordx4 v[148:151], v[132:133], off
	global_load_dwordx4 v[140:143], v[132:133], off offset:64
	global_load_dwordx4 v[136:139], v[132:133], off offset:512
	s_nop 0
	global_load_dwordx4 v[132:135], v[132:133], off offset:576
	v_lshl_add_u64 v[166:167], v[164:165], 0, v[166:167]
	s_waitcnt vmcnt(0)
	v_pk_fma_f32 v[162:163], v[162:163], s[2:3], v[46:47] op_sel_hi:[1,0,1]
	v_pk_fma_f32 v[154:155], v[154:155], s[2:3], v[42:43] op_sel_hi:[1,0,1]
	v_pk_fma_f32 v[152:153], v[152:153], s[2:3], v[40:41] op_sel_hi:[1,0,1]
	global_store_dwordx4 v[166:167], v[152:155], off offset:64
	v_pk_fma_f32 v[146:147], v[146:147], s[2:3], v[10:11] op_sel_hi:[1,0,1]
	v_pk_fma_f32 v[144:145], v[144:145], s[2:3], v[8:9] op_sel_hi:[1,0,1]
	v_pk_fma_f32 v[154:155], v[158:159], s[2:3], v[14:15] op_sel_hi:[1,0,1]
	v_pk_fma_f32 v[152:153], v[156:157], s[2:3], v[12:13] op_sel_hi:[1,0,1]
	v_pk_fma_f32 v[160:161], v[160:161], s[2:3], v[44:45] op_sel_hi:[1,0,1]
	global_store_dwordx4 v[166:167], v[152:155], off offset:512
	global_store_dwordx4 v[166:167], v[144:147], off offset:576
	v_pk_fma_f32 v[142:143], v[142:143], s[2:3], v[34:35] op_sel_hi:[1,0,1]
	v_lshl_add_u64 v[152:153], v[164:165], 0, v[196:197]
	v_pk_fma_f32 v[146:147], v[150:151], s[2:3], v[38:39] op_sel_hi:[1,0,1]
	v_pk_fma_f32 v[144:145], v[148:149], s[2:3], v[36:37] op_sel_hi:[1,0,1]
	v_pk_fma_f32 v[140:141], v[140:141], s[2:3], v[32:33] op_sel_hi:[1,0,1]
	v_pk_fma_f32 v[138:139], v[138:139], s[2:3], v[6:7] op_sel_hi:[1,0,1]
	v_pk_fma_f32 v[136:137], v[136:137], s[2:3], v[4:5] op_sel_hi:[1,0,1]
	v_pk_fma_f32 v[134:135], v[134:135], s[2:3], v[2:3] op_sel_hi:[1,0,1]
	v_pk_fma_f32 v[132:133], v[132:133], s[2:3], v[0:1] op_sel_hi:[1,0,1]
	global_store_dwordx4 v[166:167], v[160:163], off
	global_store_dwordx4 v[152:153], v[144:147], off
	global_store_dwordx4 v[152:153], v[140:143], off offset:64
	global_store_dwordx4 v[152:153], v[136:139], off offset:512
	global_store_dwordx4 v[152:153], v[132:135], off offset:576

; __device__ __forceinline__ f32x4 unpack4(u32x2 u) { f32x4 r; r[0] = bflo(u[0]); r[1] = bfhi(u[0]); r[2] = bflo(u[1]); r[3] = bfhi(u[1]); return r; }
; __device__ __forceinline__ void epilogue(const Params& p, const Unit& u, const f32x4 (&acc)[2][2][4][2], int wr, int wc, int fr, int fq) {
;     ...
;   } else if (kind >= 17) {
;     const int seg = kind - 17;
;     const bf16_t* gates = (const bf16_t*)(ws + WS_GATES);
;     float* pt = (float*)(ws + WS_PART) + (size_t)u.pm * 65536;
;     const int trow = (u.pn >> 3) * 256, tcol = (u.pn & 7) * 256;
; #pragma unroll
;     for (int ai = 0; ai < 2; ++ai)
; #pragma unroll
;       for (int mp = 0; mp < 2; ++mp) {
;         u32x2 gr[2][2][2];
; #pragma unroll
;         for (int mm = 0; mm < 2; ++mm)
; #pragma unroll
;           for (int bj = 0; bj < 2; ++bj)
; #pragma unroll
;             for (int n = 0; n < 2; ++n) {
;               const size_t row = (size_t)(trow + wr * 64 + fr + ai * 128 + (mp * 2 + mm) * 16);
;               gr[mm][bj][n] = *(const u32x2*)(gates + row * 6144 + seg * 2048 + tcol + ct0 + bj * 128 + n * 16);
;             }
; #pragma unroll
;         for (int mm = 0; mm < 2; ++mm)
; #pragma unroll
;           for (int bj = 0; bj < 2; ++bj)
; #pragma unroll
;             for (int n = 0; n < 2; ++n) {
;               const int rl = wr * 64 + fr + ai * 128 + (mp * 2 + mm) * 16;
;               *(f32x4*)(pt + rl * 256 + ct0 + bj * 128 + n * 16) = acc[ai][bj][mp * 2 + mm][n] * unpack4(gr[mm][bj][n]);
;             }
;       }
.Le3_ep:
	s_sub_i32 s30, s76, 17
	s_lshl_b32 s30, s30, 12
	s_add_u32 s34, s24, s30
	s_addc_u32 s35, s25, 0
	s_add_u32 s34, s34, 0xc709000
	s_addc_u32 s35, s35, 0
	s_lshr_b32 s31, s78, 3
	s_lshl_b32 s31, s31, 8
	s_and_b32 s29, s78, 7
	s_lshl_b32 s29, s29, 8
	v_add_u32_e32 v64, s31, v169
	v_mul_u32_u24_e32 v64, 0x3000, v64
	v_add_u32_e32 v67, s29, v174
	v_lshl_add_u32 v233, v67, 1, v64
	s_add_u32 s36, s24, 0x1f909000
	s_addc_u32 s37, s25, 0
	s_mov_b32 s30, 0xffff0000
	global_load_dwordx2 v[132:133], v233, s[34:35] offset:0
	global_load_dwordx2 v[134:135], v233, s[34:35] offset:32
	global_load_dwordx2 v[136:137], v233, s[34:35] offset:256
	global_load_dwordx2 v[138:139], v233, s[34:35] offset:288
	v_add_u32_e32 v233, 0x30000, v233
	global_load_dwordx2 v[140:141], v233, s[34:35] offset:0
	global_load_dwordx2 v[142:143], v233, s[34:35] offset:32
	global_load_dwordx2 v[144:145], v233, s[34:35] offset:256
	global_load_dwordx2 v[146:147], v233, s[34:35] offset:288
	v_add_u32_e32 v233, 0x30000, v233
	global_load_dwordx2 v[148:149], v233, s[34:35] offset:0
	global_load_dwordx2 v[150:151], v233, s[34:35] offset:32
	global_load_dwordx2 v[152:153], v233, s[34:35] offset:256
	global_load_dwordx2 v[154:155], v233, s[34:35] offset:288
	v_add_u32_e32 v233, 0x30000, v233
	global_load_dwordx2 v[156:157], v233, s[34:35] offset:0
	global_load_dwordx2 v[158:159], v233, s[34:35] offset:32
	global_load_dwordx2 v[160:161], v233, s[34:35] offset:256
	global_load_dwordx2 v[162:163], v233, s[34:35] offset:288
	v_add_u32_e32 v233, 0xf0000, v233
	global_load_dwordx2 v[164:165], v233, s[34:35] offset:0
	global_load_dwordx2 v[166:167], v233, s[34:35] offset:32
	global_load_dwordx2 v[196:197], v233, s[34:35] offset:256
	global_load_dwordx2 v[198:199], v233, s[34:35] offset:288
	v_add_u32_e32 v233, 0x30000, v233
	global_load_dwordx2 v[200:201], v233, s[34:35] offset:0
	global_load_dwordx2 v[202:203], v233, s[34:35] offset:32
	global_load_dwordx2 v[204:205], v233, s[34:35] offset:256
	global_load_dwordx2 v[206:207], v233, s[34:35] offset:288
	v_add_u32_e32 v233, 0x30000, v233
	global_load_dwordx2 v[208:209], v233, s[34:35] offset:0
	global_load_dwordx2 v[210:211], v233, s[34:35] offset:32
	global_load_dwordx2 v[212:213], v233, s[34:35] offset:256
	global_load_dwordx2 v[214:215], v233, s[34:35] offset:288
	v_add_u32_e32 v233, 0x30000, v233
	global_load_dwordx2 v[216:217], v233, s[34:35] offset:0
	global_load_dwordx2 v[218:219], v233, s[34:35] offset:32
	global_load_dwordx2 v[220:221], v233, s[34:35] offset:256
	global_load_dwordx2 v[222:223], v233, s[34:35] offset:288
	v_lshrrev_b32_e32 v64, 2, v230
	v_and_b32_e32 v67, 3, v230
	v_lshlrev_b32_e32 v224, 6, v67
	v_lshl_add_u32 v224, v64, 2, v224
	v_and_b32_e32 v225, 64, v169
	v_add_u32_e32 v225, v225, v64
	v_lshl_add_u32 v225, s48, 8, v225
	v_lshlrev_b32_e32 v225, 10, v225
	v_and_b32_e32 v232, 0x60, v174
	v_lshl_add_u32 v232, v67, 2, v232
	v_lshl_add_u32 v225, v232, 2, v225
	s_waitcnt vmcnt(31)
	v_lshlrev_b32_e32 v234, 16, v132
	v_and_b32_e32 v235, s30, v132
	v_lshlrev_b32_e32 v242, 16, v133
	v_and_b32_e32 v243, s30, v133
	v_pk_mul_f32 v[128:129], v[128:129], v[234:235]
	v_pk_mul_f32 v[130:131], v[130:131], v[242:243]
	ds_bpermute_b32 v128, v224, v128
	ds_bpermute_b32 v129, v224, v129
	ds_bpermute_b32 v130, v224, v130
	ds_bpermute_b32 v131, v224, v131
	s_waitcnt vmcnt(30)
	v_lshlrev_b32_e32 v234, 16, v134
	v_and_b32_e32 v235, s30, v134
	v_lshlrev_b32_e32 v242, 16, v135
	v_and_b32_e32 v243, s30, v135
	v_pk_mul_f32 v[124:125], v[124:125], v[234:235]
	v_pk_mul_f32 v[126:127], v[126:127], v[242:243]
	ds_bpermute_b32 v124, v224, v124
	ds_bpermute_b32 v125, v224, v125
	ds_bpermute_b32 v126, v224, v126
	ds_bpermute_b32 v127, v224, v127
	s_waitcnt lgkmcnt(4)
	global_store_dwordx4 v225, v[128:131], s[36:37] offset:0
	s_waitcnt vmcnt(30)
	v_lshlrev_b32_e32 v234, 16, v136
	v_and_b32_e32 v235, s30, v136
	v_lshlrev_b32_e32 v242, 16, v137
	v_and_b32_e32 v243, s30, v137
	v_pk_mul_f32 v[96:97], v[96:97], v[234:235]
	v_pk_mul_f32 v[98:99], v[98:99], v[242:243]
	ds_bpermute_b32 v96, v224, v96
	ds_bpermute_b32 v97, v224, v97
	ds_bpermute_b32 v98, v224, v98
	ds_bpermute_b32 v99, v224, v99
	s_waitcnt lgkmcnt(4)
	global_store_dwordx4 v225, v[124:127], s[36:37] offset:64
	s_waitcnt vmcnt(30)
	v_lshlrev_b32_e32 v234, 16, v138
	v_and_b32_e32 v235, s30, v138
	v_lshlrev_b32_e32 v242, 16, v139
	v_and_b32_e32 v243, s30, v139
	v_pk_mul_f32 v[92:93], v[92:93], v[234:235]
	v_pk_mul_f32 v[94:95], v[94:95], v[242:243]
	ds_bpermute_b32 v92, v224, v92
	ds_bpermute_b32 v93, v224, v93
	ds_bpermute_b32 v94, v224, v94
	ds_bpermute_b32 v95, v224, v95
	s_waitcnt lgkmcnt(4)
	global_store_dwordx4 v225, v[96:99], s[36:37] offset:512
	s_waitcnt vmcnt(30)
	v_lshlrev_b32_e32 v234, 16, v140
	v_and_b32_e32 v235, s30, v140
	v_lshlrev_b32_e32 v242, 16, v141
	v_and_b32_e32 v243, s30, v141
	v_pk_mul_f32 v[120:121], v[120:121], v[234:235]
	v_pk_mul_f32 v[122:123], v[122:123], v[242:243]
	ds_bpermute_b32 v120, v224, v120
	ds_bpermute_b32 v121, v224, v121
	ds_bpermute_b32 v122, v224, v122
	ds_bpermute_b32 v123, v224, v123
	s_waitcnt lgkmcnt(4)
	global_store_dwordx4 v225, v[92:95], s[36:37] offset:576
	v_add_u32_e32 v225, 0x4000, v225
	s_waitcnt vmcnt(30)
	v_lshlrev_b32_e32 v234, 16, v142
	v_and_b32_e32 v235, s30, v142
	v_lshlrev_b32_e32 v242, 16, v143
	v_and_b32_e32 v243, s30, v143
	v_pk_mul_f32 v[116:117], v[116:117], v[234:235]
	v_pk_mul_f32 v[118:119], v[118:119], v[242:243]
	ds_bpermute_b32 v116, v224, v116
	ds_bpermute_b32 v117, v224, v117
	ds_bpermute_b32 v118, v224, v118
	ds_bpermute_b32 v119, v224, v119
	s_waitcnt lgkmcnt(4)
	global_store_dwordx4 v225, v[120:123], s[36:37] offset:0
	s_waitcnt vmcnt(30)
; __device__ __forceinline__ f32x4 unpack4(u32x2 u) { f32x4 r; r[0] = bflo(u[0]); r[1] = bfhi(u[0]); r[2] = bflo(u[1]); r[3] = bfhi(u[1]); return r; }
; __device__ __forceinline__ void epilogue(const Params& p, const Unit& u, const f32x4 (&acc)[2][2][4][2], int wr, int wc, int fr, int fq) {
;     ...
; #pragma unroll
;         for (int mm = 0; mm < 2; ++mm)
; #pragma unroll
;           for (int bj = 0; bj < 2; ++bj)
; #pragma unroll
;             for (int n = 0; n < 2; ++n) {
;               const int rl = wr * 64 + fr + ai * 128 + (mp * 2 + mm) * 16;
;               *(f32x4*)(pt + rl * 256 + ct0 + bj * 128 + n * 16) = acc[ai][bj][mp * 2 + mm][n] * unpack4(gr[mm][bj][n]);
;             }
	v_lshlrev_b32_e32 v234, 16, v144
	v_and_b32_e32 v235, s30, v144
	v_lshlrev_b32_e32 v242, 16, v145
	v_and_b32_e32 v243, s30, v145
	v_pk_mul_f32 v[88:89], v[88:89], v[234:235]
	v_pk_mul_f32 v[90:91], v[90:91], v[242:243]
	ds_bpermute_b32 v88, v224, v88
	ds_bpermute_b32 v89, v224, v89
	ds_bpermute_b32 v90, v224, v90
	ds_bpermute_b32 v91, v224, v91
	s_waitcnt lgkmcnt(4)
	global_store_dwordx4 v225, v[116:119], s[36:37] offset:64
	s_waitcnt vmcnt(30)
	v_lshlrev_b32_e32 v234, 16, v146
	v_and_b32_e32 v235, s30, v146
	v_lshlrev_b32_e32 v242, 16, v147
	v_and_b32_e32 v243, s30, v147
	v_pk_mul_f32 v[84:85], v[84:85], v[234:235]
	v_pk_mul_f32 v[86:87], v[86:87], v[242:243]
	ds_bpermute_b32 v84, v224, v84
	ds_bpermute_b32 v85, v224, v85
	ds_bpermute_b32 v86, v224, v86
	ds_bpermute_b32 v87, v224, v87
	s_waitcnt lgkmcnt(4)
	global_store_dwordx4 v225, v[88:91], s[36:37] offset:512
	s_waitcnt vmcnt(30)
	v_lshlrev_b32_e32 v234, 16, v148
	v_and_b32_e32 v235, s30, v148
	v_lshlrev_b32_e32 v242, 16, v149
	v_and_b32_e32 v243, s30, v149
	v_pk_mul_f32 v[112:113], v[112:113], v[234:235]
	v_pk_mul_f32 v[114:115], v[114:115], v[242:243]
	ds_bpermute_b32 v112, v224, v112
	ds_bpermute_b32 v113, v224, v113
	ds_bpermute_b32 v114, v224, v114
	ds_bpermute_b32 v115, v224, v115
	s_waitcnt lgkmcnt(4)
	global_store_dwordx4 v225, v[84:87], s[36:37] offset:576
	v_add_u32_e32 v225, 0x4000, v225
	s_waitcnt vmcnt(30)
	v_lshlrev_b32_e32 v234, 16, v150
	v_and_b32_e32 v235, s30, v150
	v_lshlrev_b32_e32 v242, 16, v151
	v_and_b32_e32 v243, s30, v151
	v_pk_mul_f32 v[108:109], v[108:109], v[234:235]
	v_pk_mul_f32 v[110:111], v[110:111], v[242:243]
	ds_bpermute_b32 v108, v224, v108
	ds_bpermute_b32 v109, v224, v109
	ds_bpermute_b32 v110, v224, v110
	ds_bpermute_b32 v111, v224, v111
	s_waitcnt lgkmcnt(4)
	global_store_dwordx4 v225, v[112:115], s[36:37] offset:0
	s_waitcnt vmcnt(30)
	v_lshlrev_b32_e32 v234, 16, v152
	v_and_b32_e32 v235, s30, v152
	v_lshlrev_b32_e32 v242, 16, v153
	v_and_b32_e32 v243, s30, v153
	v_pk_mul_f32 v[80:81], v[80:81], v[234:235]
	v_pk_mul_f32 v[82:83], v[82:83], v[242:243]
	ds_bpermute_b32 v80, v224, v80
	ds_bpermute_b32 v81, v224, v81
	ds_bpermute_b32 v82, v224, v82
	ds_bpermute_b32 v83, v224, v83
	s_waitcnt lgkmcnt(4)
	global_store_dwordx4 v225, v[108:111], s[36:37] offset:64
	s_waitcnt vmcnt(30)
	v_lshlrev_b32_e32 v234, 16, v154
	v_and_b32_e32 v235, s30, v154
	v_lshlrev_b32_e32 v242, 16, v155
	v_and_b32_e32 v243, s30, v155
	v_pk_mul_f32 v[76:77], v[76:77], v[234:235]
	v_pk_mul_f32 v[78:79], v[78:79], v[242:243]
	ds_bpermute_b32 v76, v224, v76
	ds_bpermute_b32 v77, v224, v77
	ds_bpermute_b32 v78, v224, v78
	ds_bpermute_b32 v79, v224, v79
	s_waitcnt lgkmcnt(4)
	global_store_dwordx4 v225, v[80:83], s[36:37] offset:512
	s_waitcnt vmcnt(30)
	v_lshlrev_b32_e32 v234, 16, v156
	v_and_b32_e32 v235, s30, v156
	v_lshlrev_b32_e32 v242, 16, v157
	v_and_b32_e32 v243, s30, v157
	v_pk_mul_f32 v[104:105], v[104:105], v[234:235]
	v_pk_mul_f32 v[106:107], v[106:107], v[242:243]
	ds_bpermute_b32 v104, v224, v104
	ds_bpermute_b32 v105, v224, v105
	ds_bpermute_b32 v106, v224, v106
	ds_bpermute_b32 v107, v224, v107
	s_waitcnt lgkmcnt(4)
	global_store_dwordx4 v225, v[76:79], s[36:37] offset:576
	v_add_u32_e32 v225, 0x4000, v225
	s_waitcnt vmcnt(30)
	v_lshlrev_b32_e32 v234, 16, v158
	v_and_b32_e32 v235, s30, v158
	v_lshlrev_b32_e32 v242, 16, v159
	v_and_b32_e32 v243, s30, v159
	v_pk_mul_f32 v[100:101], v[100:101], v[234:235]
	v_pk_mul_f32 v[102:103], v[102:103], v[242:243]
	ds_bpermute_b32 v100, v224, v100
	ds_bpermute_b32 v101, v224, v101
	ds_bpermute_b32 v102, v224, v102
	ds_bpermute_b32 v103, v224, v103
	s_waitcnt lgkmcnt(4)
	global_store_dwordx4 v225, v[104:107], s[36:37] offset:0
	s_waitcnt vmcnt(30)
	v_lshlrev_b32_e32 v234, 16, v160
	v_and_b32_e32 v235, s30, v160
	v_lshlrev_b32_e32 v242, 16, v161
	v_and_b32_e32 v243, s30, v161
	v_pk_mul_f32 v[72:73], v[72:73], v[234:235]
	v_pk_mul_f32 v[74:75], v[74:75], v[242:243]
	ds_bpermute_b32 v72, v224, v72
	ds_bpermute_b32 v73, v224, v73
	ds_bpermute_b32 v74, v224, v74
	ds_bpermute_b32 v75, v224, v75
	s_waitcnt lgkmcnt(4)
	global_store_dwordx4 v225, v[100:103], s[36:37] offset:64
	s_waitcnt vmcnt(30)
	v_lshlrev_b32_e32 v234, 16, v162
	v_and_b32_e32 v235, s30, v162
	v_lshlrev_b32_e32 v242, 16, v163
	v_and_b32_e32 v243, s30, v163
	v_pk_mul_f32 v[68:69], v[68:69], v[234:235]
	v_pk_mul_f32 v[70:71], v[70:71], v[242:243]
	ds_bpermute_b32 v68, v224, v68
	ds_bpermute_b32 v69, v224, v69
	ds_bpermute_b32 v70, v224, v70
	ds_bpermute_b32 v71, v224, v71
	s_waitcnt lgkmcnt(4)
	global_store_dwordx4 v225, v[72:75], s[36:37] offset:512
	s_waitcnt vmcnt(30)
	v_lshlrev_b32_e32 v234, 16, v164
	v_and_b32_e32 v235, s30, v164
	v_lshlrev_b32_e32 v242, 16, v165
	v_and_b32_e32 v243, s30, v165
	v_pk_mul_f32 v[60:61], v[60:61], v[234:235]
	v_pk_mul_f32 v[62:63], v[62:63], v[242:243]
	ds_bpermute_b32 v60, v224, v60
	ds_bpermute_b32 v61, v224, v61
	ds_bpermute_b32 v62, v224, v62
	ds_bpermute_b32 v63, v224, v63
	s_waitcnt lgkmcnt(4)
	global_store_dwordx4 v225, v[68:71], s[36:37] offset:576
	v_add_u32_e32 v225, 0x14000, v225
	s_waitcnt vmcnt(30)
	v_lshlrev_b32_e32 v234, 16, v166
	v_and_b32_e32 v235, s30, v166
	v_lshlrev_b32_e32 v242, 16, v167
	v_and_b32_e32 v243, s30, v167
	v_pk_mul_f32 v[56:57], v[56:57], v[234:235]
	v_pk_mul_f32 v[58:59], v[58:59], v[242:243]
	ds_bpermute_b32 v56, v224, v56
	ds_bpermute_b32 v57, v224, v57
	ds_bpermute_b32 v58, v224, v58
	ds_bpermute_b32 v59, v224, v59
	s_waitcnt lgkmcnt(4)
	global_store_dwordx4 v225, v[60:63], s[36:37] offset:0
	s_waitcnt vmcnt(30)
; __device__ __forceinline__ f32x4 unpack4(u32x2 u) { f32x4 r; r[0] = bflo(u[0]); r[1] = bfhi(u[0]); r[2] = bflo(u[1]); r[3] = bfhi(u[1]); return r; }
; __device__ __forceinline__ void epilogue(const Params& p, const Unit& u, const f32x4 (&acc)[2][2][4][2], int wr, int wc, int fr, int fq) {
;     ...
; #pragma unroll
;     for (int ai = 0; ai < 2; ++ai)
; #pragma unroll
;       for (int mp = 0; mp < 2; ++mp) {
;         u32x2 gr[2][2][2];
; #pragma unroll
;         for (int mm = 0; mm < 2; ++mm)
; #pragma unroll
;           for (int bj = 0; bj < 2; ++bj)
; #pragma unroll
;             for (int n = 0; n < 2; ++n) {
;               const size_t row = (size_t)(trow + wr * 64 + fr + ai * 128 + (mp * 2 + mm) * 16);
;               gr[mm][bj][n] = *(const u32x2*)(gates + row * 6144 + seg * 2048 + tcol + ct0 + bj * 128 + n * 16);
;             }
; #pragma unroll
;         for (int mm = 0; mm < 2; ++mm)
; #pragma unroll
;           for (int bj = 0; bj < 2; ++bj)
; #pragma unroll
;             for (int n = 0; n < 2; ++n) {
;               const int rl = wr * 64 + fr + ai * 128 + (mp * 2 + mm) * 16;
;               *(f32x4*)(pt + rl * 256 + ct0 + bj * 128 + n * 16) = acc[ai][bj][mp * 2 + mm][n] * unpack4(gr[mm][bj][n]);
;             }
	v_lshlrev_b32_e32 v234, 16, v196
	v_and_b32_e32 v235, s30, v196
	v_lshlrev_b32_e32 v242, 16, v197
	v_and_b32_e32 v243, s30, v197
	v_pk_mul_f32 v[28:29], v[28:29], v[234:235]
	v_pk_mul_f32 v[30:31], v[30:31], v[242:243]
	ds_bpermute_b32 v28, v224, v28
	ds_bpermute_b32 v29, v224, v29
	ds_bpermute_b32 v30, v224, v30
	ds_bpermute_b32 v31, v224, v31
	s_waitcnt lgkmcnt(4)
	global_store_dwordx4 v225, v[56:59], s[36:37] offset:64
	s_waitcnt vmcnt(30)
	v_lshlrev_b32_e32 v234, 16, v198
	v_and_b32_e32 v235, s30, v198
	v_lshlrev_b32_e32 v242, 16, v199
	v_and_b32_e32 v243, s30, v199
	v_pk_mul_f32 v[24:25], v[24:25], v[234:235]
	v_pk_mul_f32 v[26:27], v[26:27], v[242:243]
	ds_bpermute_b32 v24, v224, v24
	ds_bpermute_b32 v25, v224, v25
	ds_bpermute_b32 v26, v224, v26
	ds_bpermute_b32 v27, v224, v27
	s_waitcnt lgkmcnt(4)
	global_store_dwordx4 v225, v[28:31], s[36:37] offset:512
	s_waitcnt vmcnt(30)
	v_lshlrev_b32_e32 v234, 16, v200
	v_and_b32_e32 v235, s30, v200
	v_lshlrev_b32_e32 v242, 16, v201
	v_and_b32_e32 v243, s30, v201
	v_pk_mul_f32 v[52:53], v[52:53], v[234:235]
	v_pk_mul_f32 v[54:55], v[54:55], v[242:243]
	ds_bpermute_b32 v52, v224, v52
	ds_bpermute_b32 v53, v224, v53
	ds_bpermute_b32 v54, v224, v54
	ds_bpermute_b32 v55, v224, v55
	s_waitcnt lgkmcnt(4)
	global_store_dwordx4 v225, v[24:27], s[36:37] offset:576
	v_add_u32_e32 v225, 0x4000, v225
	s_waitcnt vmcnt(30)
	v_lshlrev_b32_e32 v234, 16, v202
	v_and_b32_e32 v235, s30, v202
	v_lshlrev_b32_e32 v242, 16, v203
	v_and_b32_e32 v243, s30, v203
	v_pk_mul_f32 v[48:49], v[48:49], v[234:235]
	v_pk_mul_f32 v[50:51], v[50:51], v[242:243]
	ds_bpermute_b32 v48, v224, v48
	ds_bpermute_b32 v49, v224, v49
	ds_bpermute_b32 v50, v224, v50
	ds_bpermute_b32 v51, v224, v51
	s_waitcnt lgkmcnt(4)
	global_store_dwordx4 v225, v[52:55], s[36:37] offset:0
	s_waitcnt vmcnt(30)
	v_lshlrev_b32_e32 v234, 16, v204
	v_and_b32_e32 v235, s30, v204
	v_lshlrev_b32_e32 v242, 16, v205
	v_and_b32_e32 v243, s30, v205
	v_pk_mul_f32 v[20:21], v[20:21], v[234:235]
	v_pk_mul_f32 v[22:23], v[22:23], v[242:243]
	ds_bpermute_b32 v20, v224, v20
	ds_bpermute_b32 v21, v224, v21
	ds_bpermute_b32 v22, v224, v22
	ds_bpermute_b32 v23, v224, v23
	s_waitcnt lgkmcnt(4)
	global_store_dwordx4 v225, v[48:51], s[36:37] offset:64
	s_waitcnt vmcnt(30)
	v_lshlrev_b32_e32 v234, 16, v206
	v_and_b32_e32 v235, s30, v206
	v_lshlrev_b32_e32 v242, 16, v207
	v_and_b32_e32 v243, s30, v207
	v_pk_mul_f32 v[16:17], v[16:17], v[234:235]
	v_pk_mul_f32 v[18:19], v[18:19], v[242:243]
	ds_bpermute_b32 v16, v224, v16
	ds_bpermute_b32 v17, v224, v17
	ds_bpermute_b32 v18, v224, v18
	ds_bpermute_b32 v19, v224, v19
	s_waitcnt lgkmcnt(4)
	global_store_dwordx4 v225, v[20:23], s[36:37] offset:512
	s_waitcnt vmcnt(30)
	v_lshlrev_b32_e32 v234, 16, v208
	v_and_b32_e32 v235, s30, v208
	v_lshlrev_b32_e32 v242, 16, v209
	v_and_b32_e32 v243, s30, v209
	v_pk_mul_f32 v[44:45], v[44:45], v[234:235]
	v_pk_mul_f32 v[46:47], v[46:47], v[242:243]
	ds_bpermute_b32 v44, v224, v44
	ds_bpermute_b32 v45, v224, v45
	ds_bpermute_b32 v46, v224, v46
	ds_bpermute_b32 v47, v224, v47
	s_waitcnt lgkmcnt(4)
	global_store_dwordx4 v225, v[16:19], s[36:37] offset:576
	v_add_u32_e32 v225, 0x4000, v225
	s_waitcnt vmcnt(30)
	v_lshlrev_b32_e32 v234, 16, v210
	v_and_b32_e32 v235, s30, v210
	v_lshlrev_b32_e32 v242, 16, v211
	v_and_b32_e32 v243, s30, v211
	v_pk_mul_f32 v[40:41], v[40:41], v[234:235]
	v_pk_mul_f32 v[42:43], v[42:43], v[242:243]
	ds_bpermute_b32 v40, v224, v40
	ds_bpermute_b32 v41, v224, v41
	ds_bpermute_b32 v42, v224, v42
	ds_bpermute_b32 v43, v224, v43
	s_waitcnt lgkmcnt(4)
	global_store_dwordx4 v225, v[44:47], s[36:37] offset:0
	s_waitcnt vmcnt(30)
	v_lshlrev_b32_e32 v234, 16, v212
	v_and_b32_e32 v235, s30, v212
	v_lshlrev_b32_e32 v242, 16, v213
	v_and_b32_e32 v243, s30, v213
	v_pk_mul_f32 v[12:13], v[12:13], v[234:235]
	v_pk_mul_f32 v[14:15], v[14:15], v[242:243]
	ds_bpermute_b32 v12, v224, v12
	ds_bpermute_b32 v13, v224, v13
	ds_bpermute_b32 v14, v224, v14
	ds_bpermute_b32 v15, v224, v15
	s_waitcnt lgkmcnt(4)
	global_store_dwordx4 v225, v[40:43], s[36:37] offset:64
	s_waitcnt vmcnt(30)
	v_lshlrev_b32_e32 v234, 16, v214
	v_and_b32_e32 v235, s30, v214
	v_lshlrev_b32_e32 v242, 16, v215
	v_and_b32_e32 v243, s30, v215
	v_pk_mul_f32 v[8:9], v[8:9], v[234:235]
	v_pk_mul_f32 v[10:11], v[10:11], v[242:243]
	ds_bpermute_b32 v8, v224, v8
	ds_bpermute_b32 v9, v224, v9
	ds_bpermute_b32 v10, v224, v10
	ds_bpermute_b32 v11, v224, v11
	s_waitcnt lgkmcnt(4)
	global_store_dwordx4 v225, v[12:15], s[36:37] offset:512
	s_waitcnt vmcnt(30)
	v_lshlrev_b32_e32 v234, 16, v216
	v_and_b32_e32 v235, s30, v216
	v_lshlrev_b32_e32 v242, 16, v217
	v_and_b32_e32 v243, s30, v217
	v_pk_mul_f32 v[36:37], v[36:37], v[234:235]
	v_pk_mul_f32 v[38:39], v[38:39], v[242:243]
	ds_bpermute_b32 v36, v224, v36
	ds_bpermute_b32 v37, v224, v37
	ds_bpermute_b32 v38, v224, v38
	ds_bpermute_b32 v39, v224, v39
	s_waitcnt lgkmcnt(4)
	global_store_dwordx4 v225, v[8:11], s[36:37] offset:576
	v_add_u32_e32 v225, 0x4000, v225
	s_waitcnt vmcnt(30)
	v_lshlrev_b32_e32 v234, 16, v218
	v_and_b32_e32 v235, s30, v218
	v_lshlrev_b32_e32 v242, 16, v219
	v_and_b32_e32 v243, s30, v219
	v_pk_mul_f32 v[32:33], v[32:33], v[234:235]
	v_pk_mul_f32 v[34:35], v[34:35], v[242:243]
	ds_bpermute_b32 v32, v224, v32
	ds_bpermute_b32 v33, v224, v33
	ds_bpermute_b32 v34, v224, v34
	ds_bpermute_b32 v35, v224, v35
	s_waitcnt lgkmcnt(4)
	global_store_dwordx4 v225, v[36:39], s[36:37] offset:0
	s_waitcnt vmcnt(30)
	v_lshlrev_b32_e32 v234, 16, v220
	v_and_b32_e32 v235, s30, v220
	v_lshlrev_b32_e32 v242, 16, v221
	v_and_b32_e32 v243, s30, v221
	v_pk_mul_f32 v[4:5], v[4:5], v[234:235]
	v_pk_mul_f32 v[6:7], v[6:7], v[242:243]
	ds_bpermute_b32 v4, v224, v4
	ds_bpermute_b32 v5, v224, v5
	ds_bpermute_b32 v6, v224, v6
	ds_bpermute_b32 v7, v224, v7
	s_waitcnt lgkmcnt(4)
	global_store_dwordx4 v225, v[32:35], s[36:37] offset:64
	s_waitcnt vmcnt(30)
	v_lshlrev_b32_e32 v234, 16, v222
	v_and_b32_e32 v235, s30, v222
	v_lshlrev_b32_e32 v242, 16, v223
	v_and_b32_e32 v243, s30, v223
	v_pk_mul_f32 v[0:1], v[0:1], v[234:235]
	v_pk_mul_f32 v[2:3], v[2:3], v[242:243]
	ds_bpermute_b32 v0, v224, v0
	ds_bpermute_b32 v1, v224, v1
	ds_bpermute_b32 v2, v224, v2
	ds_bpermute_b32 v3, v224, v3
	s_waitcnt lgkmcnt(4)
	global_store_dwordx4 v225, v[4:7], s[36:37] offset:512
	s_waitcnt lgkmcnt(0)
	global_store_dwordx4 v225, v[0:3], s[36:37] offset:576
	s_branch .LBB0_987
; __device__ __forceinline__ void epilogue(const Params& p, const Unit& u, const f32x4 (&acc)[2][2][4][2], int wr, int wc, int fr, int fq) {
;     ...
;   } else {
;     const float* x1 = (const float*)(ws + WS_X1);
;     float* yo = (float*)(ws + WS_YPRE);
;     const int cb = u.pn * 256 + ct0;
; #pragma unroll
;     for (int ai = 0; ai < 2; ++ai)
; #pragma unroll
;       for (int mp = 0; mp < 2; ++mp) {
;         f32x4 xv[2][2][2];
; #pragma unroll
;         for (int mm = 0; mm < 2; ++mm) {
;           const size_t row = (size_t)(row0 + ai * 128 + (mp * 2 + mm) * 16);
; #pragma unroll
;           for (int bj = 0; bj < 2; ++bj)
; #pragma unroll
;             for (int n = 0; n < 2; ++n) xv[mm][bj][n] = *(const f32x4*)(x1 + row * 2048 + cb + bj * 128 + n * 16);
;         }
; #pragma unroll
;         for (int mm = 0; mm < 2; ++mm) {
;           const size_t row = (size_t)(row0 + ai * 128 + (mp * 2 + mm) * 16);
; #pragma unroll
;           for (int bj = 0; bj < 2; ++bj)
; #pragma unroll
;             for (int n = 0; n < 2; ++n) *(f32x4*)(yo + row * 2048 + cb + bj * 128 + n * 16) = xv[mm][bj][n] * ALPHA + acc[ai][bj][mp * 2 + mm][n];
;         }
;       }
.Le14_ep:
	s_add_u32 s34, s24, 0x109000
	s_addc_u32 s35, s25, 0
	s_add_u32 s36, s24, 0x13309000
	s_addc_u32 s37, s25, 0
	v_lshl_add_u32 v233, v66, 13, 0
	s_mov_b32 s30, 0x3f9837f0
	v_lshl_or_b32 v64, s78, 8, v174
	v_lshl_add_u32 v233, v64, 2, v233
	v_add_u32_e32 v235, 0x100000, v233
	global_load_dwordx4 v[132:135], v233, s[34:35] offset:0
	global_load_dwordx4 v[136:139], v233, s[34:35] offset:64
	global_load_dwordx4 v[140:143], v233, s[34:35] offset:512
	global_load_dwordx4 v[144:147], v233, s[34:35] offset:576
	v_add_u32_e32 v233, 0x20000, v233
	global_load_dwordx4 v[148:151], v233, s[34:35] offset:0
	global_load_dwordx4 v[152:155], v233, s[34:35] offset:64
	global_load_dwordx4 v[156:159], v233, s[34:35] offset:512
	global_load_dwordx4 v[160:163], v233, s[34:35] offset:576
	v_add_u32_e32 v233, 0x20000, v233
	global_load_dwordx4 v[164:167], v233, s[34:35] offset:0
	global_load_dwordx4 v[196:199], v233, s[34:35] offset:64
	global_load_dwordx4 v[200:203], v233, s[34:35] offset:512
	global_load_dwordx4 v[204:207], v233, s[34:35] offset:576
	v_add_u32_e32 v233, 0x20000, v233
	global_load_dwordx4 v[208:211], v233, s[34:35] offset:0
	global_load_dwordx4 v[212:215], v233, s[34:35] offset:64
	global_load_dwordx4 v[216:219], v233, s[34:35] offset:512
	global_load_dwordx4 v[220:223], v233, s[34:35] offset:576
	v_lshrrev_b32_e32 v64, 2, v230
	v_and_b32_e32 v67, 3, v230
	v_lshlrev_b32_e32 v224, 6, v67
	v_lshl_add_u32 v224, v64, 2, v224
	v_and_b32_e32 v225, 64, v169
	v_add_u32_e32 v225, v225, v64
	v_lshl_add_u32 v225, s48, 8, v225
	v_lshlrev_b32_e32 v225, 13, v225
	v_and_b32_e32 v232, 0x60, v174
	v_lshl_add_u32 v232, v67, 2, v232
	v_lshl_or_b32 v64, s78, 8, v232
	v_lshl_add_u32 v225, v64, 2, v225
	s_waitcnt vmcnt(15)
	v_fmac_f32_e32 v128, s30, v132
	v_fmac_f32_e32 v129, s30, v133
	v_fmac_f32_e32 v130, s30, v134
	v_fmac_f32_e32 v131, s30, v135
	global_load_dwordx4 v[132:135], v235, s[34:35] offset:0
	ds_bpermute_b32 v128, v224, v128
	ds_bpermute_b32 v129, v224, v129
	ds_bpermute_b32 v130, v224, v130
	ds_bpermute_b32 v131, v224, v131
	s_waitcnt vmcnt(15)
	v_fmac_f32_e32 v124, s30, v136
	v_fmac_f32_e32 v125, s30, v137
	v_fmac_f32_e32 v126, s30, v138
	v_fmac_f32_e32 v127, s30, v139
	global_load_dwordx4 v[136:139], v235, s[34:35] offset:64
	ds_bpermute_b32 v124, v224, v124
	ds_bpermute_b32 v125, v224, v125
	ds_bpermute_b32 v126, v224, v126
	ds_bpermute_b32 v127, v224, v127
	s_waitcnt lgkmcnt(4)
	global_store_dwordx4 v225, v[128:131], s[36:37] offset:0
	s_waitcnt vmcnt(16)
	v_fmac_f32_e32 v96, s30, v140
	v_fmac_f32_e32 v97, s30, v141
	v_fmac_f32_e32 v98, s30, v142
	v_fmac_f32_e32 v99, s30, v143
	global_load_dwordx4 v[140:143], v235, s[34:35] offset:512
	ds_bpermute_b32 v96, v224, v96
	ds_bpermute_b32 v97, v224, v97
	ds_bpermute_b32 v98, v224, v98
	ds_bpermute_b32 v99, v224, v99
	s_waitcnt lgkmcnt(4)
	global_store_dwordx4 v225, v[124:127], s[36:37] offset:64
	s_waitcnt vmcnt(17)
	v_fmac_f32_e32 v92, s30, v144
	v_fmac_f32_e32 v93, s30, v145
	v_fmac_f32_e32 v94, s30, v146
	v_fmac_f32_e32 v95, s30, v147
	global_load_dwordx4 v[144:147], v235, s[34:35] offset:576
	v_add_u32_e32 v235, 0x20000, v235
	ds_bpermute_b32 v92, v224, v92
	ds_bpermute_b32 v93, v224, v93
	ds_bpermute_b32 v94, v224, v94
	ds_bpermute_b32 v95, v224, v95
	s_waitcnt lgkmcnt(4)
	global_store_dwordx4 v225, v[96:99], s[36:37] offset:512
	s_waitcnt vmcnt(18)
	v_fmac_f32_e32 v120, s30, v148
	v_fmac_f32_e32 v121, s30, v149
	v_fmac_f32_e32 v122, s30, v150
	v_fmac_f32_e32 v123, s30, v151
	global_load_dwordx4 v[148:151], v235, s[34:35] offset:0
	ds_bpermute_b32 v120, v224, v120
	ds_bpermute_b32 v121, v224, v121
	ds_bpermute_b32 v122, v224, v122
	ds_bpermute_b32 v123, v224, v123
	s_waitcnt lgkmcnt(4)
	global_store_dwordx4 v225, v[92:95], s[36:37] offset:576
	v_add_u32_e32 v225, 0x20000, v225
	s_waitcnt vmcnt(19)
	v_fmac_f32_e32 v116, s30, v152
	v_fmac_f32_e32 v117, s30, v153
	v_fmac_f32_e32 v118, s30, v154
	v_fmac_f32_e32 v119, s30, v155
	global_load_dwordx4 v[152:155], v235, s[34:35] offset:64
	ds_bpermute_b32 v116, v224, v116
	ds_bpermute_b32 v117, v224, v117
	ds_bpermute_b32 v118, v224, v118
	ds_bpermute_b32 v119, v224, v119
	s_waitcnt lgkmcnt(4)
	global_store_dwordx4 v225, v[120:123], s[36:37] offset:0
	s_waitcnt vmcnt(20)
	v_fmac_f32_e32 v88, s30, v156
	v_fmac_f32_e32 v89, s30, v157
	v_fmac_f32_e32 v90, s30, v158
	v_fmac_f32_e32 v91, s30, v159
	global_load_dwordx4 v[156:159], v235, s[34:35] offset:512
	ds_bpermute_b32 v88, v224, v88
	ds_bpermute_b32 v89, v224, v89
	ds_bpermute_b32 v90, v224, v90
	ds_bpermute_b32 v91, v224, v91
	s_waitcnt lgkmcnt(4)
	global_store_dwordx4 v225, v[116:119], s[36:37] offset:64
	s_waitcnt vmcnt(21)
	v_fmac_f32_e32 v84, s30, v160
	v_fmac_f32_e32 v85, s30, v161
	v_fmac_f32_e32 v86, s30, v162
	v_fmac_f32_e32 v87, s30, v163
	global_load_dwordx4 v[160:163], v235, s[34:35] offset:576
	v_add_u32_e32 v235, 0x20000, v235
	ds_bpermute_b32 v84, v224, v84
	ds_bpermute_b32 v85, v224, v85
	ds_bpermute_b32 v86, v224, v86
	ds_bpermute_b32 v87, v224, v87
	s_waitcnt lgkmcnt(4)
	global_store_dwordx4 v225, v[88:91], s[36:37] offset:512
	s_waitcnt vmcnt(22)
	v_fmac_f32_e32 v112, s30, v164
	v_fmac_f32_e32 v113, s30, v165
	v_fmac_f32_e32 v114, s30, v166
	v_fmac_f32_e32 v115, s30, v167
	global_load_dwordx4 v[164:167], v235, s[34:35] offset:0
	ds_bpermute_b32 v112, v224, v112
	ds_bpermute_b32 v113, v224, v113
	ds_bpermute_b32 v114, v224, v114
	ds_bpermute_b32 v115, v224, v115
	s_waitcnt lgkmcnt(4)
	global_store_dwordx4 v225, v[84:87], s[36:37] offset:576
	v_add_u32_e32 v225, 0x20000, v225
	s_waitcnt vmcnt(23)
; __device__ __forceinline__ void epilogue(const Params& p, const Unit& u, const f32x4 (&acc)[2][2][4][2], int wr, int wc, int fr, int fq) {
;     ...
;   } else {
;     const float* x1 = (const float*)(ws + WS_X1);
;     float* yo = (float*)(ws + WS_YPRE);
;     const int cb = u.pn * 256 + ct0;
; #pragma unroll
;     for (int ai = 0; ai < 2; ++ai)
; #pragma unroll
;       for (int mp = 0; mp < 2; ++mp) {
;         f32x4 xv[2][2][2];
; #pragma unroll
;         for (int mm = 0; mm < 2; ++mm) {
;           const size_t row = (size_t)(row0 + ai * 128 + (mp * 2 + mm) * 16);
; #pragma unroll
;           for (int bj = 0; bj < 2; ++bj)
; #pragma unroll
;             for (int n = 0; n < 2; ++n) xv[mm][bj][n] = *(const f32x4*)(x1 + row * 2048 + cb + bj * 128 + n * 16);
;         }
; #pragma unroll
;         for (int mm = 0; mm < 2; ++mm) {
;           const size_t row = (size_t)(row0 + ai * 128 + (mp * 2 + mm) * 16);
; #pragma unroll
;           for (int bj = 0; bj < 2; ++bj)
; #pragma unroll
;             for (int n = 0; n < 2; ++n) *(f32x4*)(yo + row * 2048 + cb + bj * 128 + n * 16) = xv[mm][bj][n] * ALPHA + acc[ai][bj][mp * 2 + mm][n];
;         }
;       }
	v_fmac_f32_e32 v108, s30, v196
	v_fmac_f32_e32 v109, s30, v197
	v_fmac_f32_e32 v110, s30, v198
	v_fmac_f32_e32 v111, s30, v199
	global_load_dwordx4 v[196:199], v235, s[34:35] offset:64
	ds_bpermute_b32 v108, v224, v108
	ds_bpermute_b32 v109, v224, v109
	ds_bpermute_b32 v110, v224, v110
	ds_bpermute_b32 v111, v224, v111
	s_waitcnt lgkmcnt(4)
	global_store_dwordx4 v225, v[112:115], s[36:37] offset:0
	s_waitcnt vmcnt(24)
	v_fmac_f32_e32 v80, s30, v200
	v_fmac_f32_e32 v81, s30, v201
	v_fmac_f32_e32 v82, s30, v202
	v_fmac_f32_e32 v83, s30, v203
	global_load_dwordx4 v[200:203], v235, s[34:35] offset:512
	ds_bpermute_b32 v80, v224, v80
	ds_bpermute_b32 v81, v224, v81
	ds_bpermute_b32 v82, v224, v82
	ds_bpermute_b32 v83, v224, v83
	s_waitcnt lgkmcnt(4)
	global_store_dwordx4 v225, v[108:111], s[36:37] offset:64
	s_waitcnt vmcnt(25)
	v_fmac_f32_e32 v76, s30, v204
	v_fmac_f32_e32 v77, s30, v205
	v_fmac_f32_e32 v78, s30, v206
	v_fmac_f32_e32 v79, s30, v207
	global_load_dwordx4 v[204:207], v235, s[34:35] offset:576
	v_add_u32_e32 v235, 0x20000, v235
	ds_bpermute_b32 v76, v224, v76
	ds_bpermute_b32 v77, v224, v77
	ds_bpermute_b32 v78, v224, v78
	ds_bpermute_b32 v79, v224, v79
	s_waitcnt lgkmcnt(4)
	global_store_dwordx4 v225, v[80:83], s[36:37] offset:512
	s_waitcnt vmcnt(26)
	v_fmac_f32_e32 v104, s30, v208
	v_fmac_f32_e32 v105, s30, v209
	v_fmac_f32_e32 v106, s30, v210
	v_fmac_f32_e32 v107, s30, v211
	global_load_dwordx4 v[208:211], v235, s[34:35] offset:0
	ds_bpermute_b32 v104, v224, v104
	ds_bpermute_b32 v105, v224, v105
	ds_bpermute_b32 v106, v224, v106
	ds_bpermute_b32 v107, v224, v107
	s_waitcnt lgkmcnt(4)
	global_store_dwordx4 v225, v[76:79], s[36:37] offset:576
	v_add_u32_e32 v225, 0x20000, v225
	s_waitcnt vmcnt(27)
	v_fmac_f32_e32 v100, s30, v212
	v_fmac_f32_e32 v101, s30, v213
	v_fmac_f32_e32 v102, s30, v214
	v_fmac_f32_e32 v103, s30, v215
	global_load_dwordx4 v[212:215], v235, s[34:35] offset:64
	ds_bpermute_b32 v100, v224, v100
	ds_bpermute_b32 v101, v224, v101
	ds_bpermute_b32 v102, v224, v102
	ds_bpermute_b32 v103, v224, v103
	s_waitcnt lgkmcnt(4)
	global_store_dwordx4 v225, v[104:107], s[36:37] offset:0
	s_waitcnt vmcnt(28)
	v_fmac_f32_e32 v72, s30, v216
	v_fmac_f32_e32 v73, s30, v217
	v_fmac_f32_e32 v74, s30, v218
	v_fmac_f32_e32 v75, s30, v219
	global_load_dwordx4 v[216:219], v235, s[34:35] offset:512
	ds_bpermute_b32 v72, v224, v72
	ds_bpermute_b32 v73, v224, v73
	ds_bpermute_b32 v74, v224, v74
	ds_bpermute_b32 v75, v224, v75
	s_waitcnt lgkmcnt(4)
	global_store_dwordx4 v225, v[100:103], s[36:37] offset:64
	s_waitcnt vmcnt(29)
	v_fmac_f32_e32 v68, s30, v220
	v_fmac_f32_e32 v69, s30, v221
	v_fmac_f32_e32 v70, s30, v222
	v_fmac_f32_e32 v71, s30, v223
	global_load_dwordx4 v[220:223], v235, s[34:35] offset:576
	ds_bpermute_b32 v68, v224, v68
	ds_bpermute_b32 v69, v224, v69
	ds_bpermute_b32 v70, v224, v70
	ds_bpermute_b32 v71, v224, v71
	s_waitcnt lgkmcnt(4)
	global_store_dwordx4 v225, v[72:75], s[36:37] offset:512
	s_waitcnt vmcnt(30)
	v_fmac_f32_e32 v60, s30, v132
	v_fmac_f32_e32 v61, s30, v133
	v_fmac_f32_e32 v62, s30, v134
	v_fmac_f32_e32 v63, s30, v135
	ds_bpermute_b32 v60, v224, v60
	ds_bpermute_b32 v61, v224, v61
	ds_bpermute_b32 v62, v224, v62
	ds_bpermute_b32 v63, v224, v63
	s_waitcnt lgkmcnt(4)
	global_store_dwordx4 v225, v[68:71], s[36:37] offset:576
	v_add_u32_e32 v225, 0xa0000, v225
	s_waitcnt vmcnt(30)
	v_fmac_f32_e32 v56, s30, v136
	v_fmac_f32_e32 v57, s30, v137
	v_fmac_f32_e32 v58, s30, v138
	v_fmac_f32_e32 v59, s30, v139
	ds_bpermute_b32 v56, v224, v56
	ds_bpermute_b32 v57, v224, v57
	ds_bpermute_b32 v58, v224, v58
	ds_bpermute_b32 v59, v224, v59
	s_waitcnt lgkmcnt(4)
	global_store_dwordx4 v225, v[60:63], s[36:37] offset:0
	s_waitcnt vmcnt(29)
	v_fmac_f32_e32 v28, s30, v140
	v_fmac_f32_e32 v29, s30, v141
	v_fmac_f32_e32 v30, s30, v142
	v_fmac_f32_e32 v31, s30, v143
	ds_bpermute_b32 v28, v224, v28
	ds_bpermute_b32 v29, v224, v29
	ds_bpermute_b32 v30, v224, v30
	ds_bpermute_b32 v31, v224, v31
	s_waitcnt lgkmcnt(4)
	global_store_dwordx4 v225, v[56:59], s[36:37] offset:64
	s_waitcnt vmcnt(28)
	v_fmac_f32_e32 v24, s30, v144
	v_fmac_f32_e32 v25, s30, v145
	v_fmac_f32_e32 v26, s30, v146
	v_fmac_f32_e32 v27, s30, v147
	ds_bpermute_b32 v24, v224, v24
	ds_bpermute_b32 v25, v224, v25
	ds_bpermute_b32 v26, v224, v26
	ds_bpermute_b32 v27, v224, v27
	s_waitcnt lgkmcnt(4)
	global_store_dwordx4 v225, v[28:31], s[36:37] offset:512
	s_waitcnt vmcnt(27)
	v_fmac_f32_e32 v52, s30, v148
	v_fmac_f32_e32 v53, s30, v149
	v_fmac_f32_e32 v54, s30, v150
	v_fmac_f32_e32 v55, s30, v151
	ds_bpermute_b32 v52, v224, v52
	ds_bpermute_b32 v53, v224, v53
	ds_bpermute_b32 v54, v224, v54
	ds_bpermute_b32 v55, v224, v55
	s_waitcnt lgkmcnt(4)
	global_store_dwordx4 v225, v[24:27], s[36:37] offset:576
	v_add_u32_e32 v225, 0x20000, v225
	s_waitcnt vmcnt(26)
	v_fmac_f32_e32 v48, s30, v152
	v_fmac_f32_e32 v49, s30, v153
	v_fmac_f32_e32 v50, s30, v154
	v_fmac_f32_e32 v51, s30, v155
	ds_bpermute_b32 v48, v224, v48
	ds_bpermute_b32 v49, v224, v49
	ds_bpermute_b32 v50, v224, v50
	ds_bpermute_b32 v51, v224, v51
	s_waitcnt lgkmcnt(4)
	global_store_dwordx4 v225, v[52:55], s[36:37] offset:0
	s_waitcnt vmcnt(25)
	v_fmac_f32_e32 v20, s30, v156
	v_fmac_f32_e32 v21, s30, v157
	v_fmac_f32_e32 v22, s30, v158
	v_fmac_f32_e32 v23, s30, v159
	ds_bpermute_b32 v20, v224, v20
	ds_bpermute_b32 v21, v224, v21
	ds_bpermute_b32 v22, v224, v22
	ds_bpermute_b32 v23, v224, v23
	s_waitcnt lgkmcnt(4)
	global_store_dwordx4 v225, v[48:51], s[36:37] offset:64
	s_waitcnt vmcnt(24)
; __device__ __forceinline__ void epilogue(const Params& p, const Unit& u, const f32x4 (&acc)[2][2][4][2], int wr, int wc, int fr, int fq) {
;     ...
;   } else if (kind == 12) {
;     float* xo = (float*)(ws + WS_X1);
;     const int cb = u.pn * 256 + ct0;
; #pragma unroll
;     for (int ai = 0; ai < 2; ++ai)
; #pragma unroll
;       for (int mp = 0; mp < 2; ++mp) {
;         f32x4 xv[2][2][2];
; #pragma unroll
;         for (int mm = 0; mm < 2; ++mm) {
;           const int row = row0 + ai * 128 + (mp * 2 + mm) * 16;
;           const float* xr = row < TOKP ? p.in[0] + (size_t)row * 2048 : p.in[1] + (size_t)(row - TOKP) * 2048;
; #pragma unroll
;           for (int bj = 0; bj < 2; ++bj)
; #pragma unroll
;             for (int n = 0; n < 2; ++n) xv[mm][bj][n] = *(const f32x4*)(xr + cb + bj * 128 + n * 16);
;         }
; #pragma unroll
;         for (int mm = 0; mm < 2; ++mm) {
;           const int row = row0 + ai * 128 + (mp * 2 + mm) * 16;
; #pragma unroll
;           for (int bj = 0; bj < 2; ++bj)
; #pragma unroll
;             for (int n = 0; n < 2; ++n) *(f32x4*)(xo + (size_t)row * 2048 + cb + bj * 128 + n * 16) = xv[mm][bj][n] * ALPHA + acc[ai][bj][mp * 2 + mm][n];
;         }
;       }
;     ...
;   } else {
;     const float* x1 = (const float*)(ws + WS_X1);
;     float* yo = (float*)(ws + WS_YPRE);
;     const int cb = u.pn * 256 + ct0;
; #pragma unroll
;     for (int ai = 0; ai < 2; ++ai)
; #pragma unroll
;       for (int mp = 0; mp < 2; ++mp) {
;         f32x4 xv[2][2][2];
; #pragma unroll
;         for (int mm = 0; mm < 2; ++mm) {
;           const size_t row = (size_t)(row0 + ai * 128 + (mp * 2 + mm) * 16);
; #pragma unroll
;           for (int bj = 0; bj < 2; ++bj)
; #pragma unroll
;             for (int n = 0; n < 2; ++n) xv[mm][bj][n] = *(const f32x4*)(x1 + row * 2048 + cb + bj * 128 + n * 16);
;         }
; #pragma unroll
;         for (int mm = 0; mm < 2; ++mm) {
;           const size_t row = (size_t)(row0 + ai * 128 + (mp * 2 + mm) * 16);
; #pragma unroll
;           for (int bj = 0; bj < 2; ++bj)
; #pragma unroll
;             for (int n = 0; n < 2; ++n) *(f32x4*)(yo + row * 2048 + cb + bj * 128 + n * 16) = xv[mm][bj][n] * ALPHA + acc[ai][bj][mp * 2 + mm][n];
;         }
;       }
	v_fmac_f32_e32 v16, s30, v160
	v_fmac_f32_e32 v17, s30, v161
	v_fmac_f32_e32 v18, s30, v162
	v_fmac_f32_e32 v19, s30, v163
	ds_bpermute_b32 v16, v224, v16
	ds_bpermute_b32 v17, v224, v17
	ds_bpermute_b32 v18, v224, v18
	ds_bpermute_b32 v19, v224, v19
	s_waitcnt lgkmcnt(4)
	global_store_dwordx4 v225, v[20:23], s[36:37] offset:512
	s_waitcnt vmcnt(23)
	v_fmac_f32_e32 v44, s30, v164
	v_fmac_f32_e32 v45, s30, v165
	v_fmac_f32_e32 v46, s30, v166
	v_fmac_f32_e32 v47, s30, v167
	ds_bpermute_b32 v44, v224, v44
	ds_bpermute_b32 v45, v224, v45
	ds_bpermute_b32 v46, v224, v46
	ds_bpermute_b32 v47, v224, v47
	s_waitcnt lgkmcnt(4)
	global_store_dwordx4 v225, v[16:19], s[36:37] offset:576
	v_add_u32_e32 v225, 0x20000, v225
	s_waitcnt vmcnt(22)
	v_fmac_f32_e32 v40, s30, v196
	v_fmac_f32_e32 v41, s30, v197
	v_fmac_f32_e32 v42, s30, v198
	v_fmac_f32_e32 v43, s30, v199
	ds_bpermute_b32 v40, v224, v40
	ds_bpermute_b32 v41, v224, v41
	ds_bpermute_b32 v42, v224, v42
	ds_bpermute_b32 v43, v224, v43
	s_waitcnt lgkmcnt(4)
	global_store_dwordx4 v225, v[44:47], s[36:37] offset:0
	s_waitcnt vmcnt(21)
	v_fmac_f32_e32 v12, s30, v200
	v_fmac_f32_e32 v13, s30, v201
	v_fmac_f32_e32 v14, s30, v202
	v_fmac_f32_e32 v15, s30, v203
	ds_bpermute_b32 v12, v224, v12
	ds_bpermute_b32 v13, v224, v13
	ds_bpermute_b32 v14, v224, v14
	ds_bpermute_b32 v15, v224, v15
	s_waitcnt lgkmcnt(4)
	global_store_dwordx4 v225, v[40:43], s[36:37] offset:64
	s_waitcnt vmcnt(20)
	v_fmac_f32_e32 v8, s30, v204
	v_fmac_f32_e32 v9, s30, v205
	v_fmac_f32_e32 v10, s30, v206
	v_fmac_f32_e32 v11, s30, v207
	ds_bpermute_b32 v8, v224, v8
	ds_bpermute_b32 v9, v224, v9
	ds_bpermute_b32 v10, v224, v10
	ds_bpermute_b32 v11, v224, v11
	s_waitcnt lgkmcnt(4)
	global_store_dwordx4 v225, v[12:15], s[36:37] offset:512
	s_waitcnt vmcnt(19)
	v_fmac_f32_e32 v36, s30, v208
	v_fmac_f32_e32 v37, s30, v209
	v_fmac_f32_e32 v38, s30, v210
	v_fmac_f32_e32 v39, s30, v211
	ds_bpermute_b32 v36, v224, v36
	ds_bpermute_b32 v37, v224, v37
	ds_bpermute_b32 v38, v224, v38
	ds_bpermute_b32 v39, v224, v39
	s_waitcnt lgkmcnt(4)
	global_store_dwordx4 v225, v[8:11], s[36:37] offset:576
	v_add_u32_e32 v225, 0x20000, v225
	s_waitcnt vmcnt(18)
	v_fmac_f32_e32 v32, s30, v212
	v_fmac_f32_e32 v33, s30, v213
	v_fmac_f32_e32 v34, s30, v214
	v_fmac_f32_e32 v35, s30, v215
	ds_bpermute_b32 v32, v224, v32
	ds_bpermute_b32 v33, v224, v33
	ds_bpermute_b32 v34, v224, v34
	ds_bpermute_b32 v35, v224, v35
	s_waitcnt lgkmcnt(4)
	global_store_dwordx4 v225, v[36:39], s[36:37] offset:0
	s_waitcnt vmcnt(17)
	v_fmac_f32_e32 v4, s30, v216
	v_fmac_f32_e32 v5, s30, v217
	v_fmac_f32_e32 v6, s30, v218
	v_fmac_f32_e32 v7, s30, v219
	ds_bpermute_b32 v4, v224, v4
	ds_bpermute_b32 v5, v224, v5
	ds_bpermute_b32 v6, v224, v6
	ds_bpermute_b32 v7, v224, v7
	s_waitcnt lgkmcnt(4)
	global_store_dwordx4 v225, v[32:35], s[36:37] offset:64
	s_waitcnt vmcnt(16)
	v_fmac_f32_e32 v0, s30, v220
	v_fmac_f32_e32 v1, s30, v221
	v_fmac_f32_e32 v2, s30, v222
	v_fmac_f32_e32 v3, s30, v223
	ds_bpermute_b32 v0, v224, v0
	ds_bpermute_b32 v1, v224, v1
	ds_bpermute_b32 v2, v224, v2
	ds_bpermute_b32 v3, v224, v3
	s_waitcnt lgkmcnt(4)
	global_store_dwordx4 v225, v[4:7], s[36:37] offset:512
	s_waitcnt lgkmcnt(0)
	global_store_dwordx4 v225, v[0:3], s[36:37] offset:576
	s_branch .LBB0_987
.Le12_ep:
	s_add_u32 s36, s24, 0x109000
	s_addc_u32 s37, s25, 0
	s_mov_b64 s[34:35], s[4:5]
	v_mov_b32_e32 v64, v66
	s_cmp_lt_u32 s48, 32
	s_cbranch_scc1 .Le12_ep_p
	s_mov_b64 s[34:35], s[6:7]
	v_add_u32_e32 v64, 0xffffe000, v66
.Le12_ep_p:
	v_lshlrev_b32_e32 v233, 13, v64
	s_mov_b32 s30, 0x3f9837f0
	v_lshl_or_b32 v64, s78, 8, v174
	v_lshl_add_u32 v233, v64, 2, v233
	v_add_u32_e32 v235, 0x100000, v233
	global_load_dwordx4 v[132:135], v233, s[34:35] offset:0
	global_load_dwordx4 v[136:139], v233, s[34:35] offset:64
	global_load_dwordx4 v[140:143], v233, s[34:35] offset:512
	global_load_dwordx4 v[144:147], v233, s[34:35] offset:576
	v_add_u32_e32 v233, 0x20000, v233
	global_load_dwordx4 v[148:151], v233, s[34:35] offset:0
	global_load_dwordx4 v[152:155], v233, s[34:35] offset:64
	global_load_dwordx4 v[156:159], v233, s[34:35] offset:512
	global_load_dwordx4 v[160:163], v233, s[34:35] offset:576
	v_add_u32_e32 v233, 0x20000, v233
	global_load_dwordx4 v[164:167], v233, s[34:35] offset:0
	global_load_dwordx4 v[196:199], v233, s[34:35] offset:64
	global_load_dwordx4 v[200:203], v233, s[34:35] offset:512
	global_load_dwordx4 v[204:207], v233, s[34:35] offset:576
	v_add_u32_e32 v233, 0x20000, v233
	global_load_dwordx4 v[208:211], v233, s[34:35] offset:0
	global_load_dwordx4 v[212:215], v233, s[34:35] offset:64
	global_load_dwordx4 v[216:219], v233, s[34:35] offset:512
	global_load_dwordx4 v[220:223], v233, s[34:35] offset:576
	v_lshrrev_b32_e32 v64, 2, v230
	v_and_b32_e32 v67, 3, v230
	v_lshlrev_b32_e32 v224, 6, v67
	v_lshl_add_u32 v224, v64, 2, v224
	v_and_b32_e32 v225, 64, v169
	v_add_u32_e32 v225, v225, v64
	v_lshl_add_u32 v225, s48, 8, v225
	v_lshlrev_b32_e32 v225, 13, v225
	v_and_b32_e32 v232, 0x60, v174
	v_lshl_add_u32 v232, v67, 2, v232
	v_lshl_or_b32 v64, s78, 8, v232
	v_lshl_add_u32 v225, v64, 2, v225
	s_waitcnt vmcnt(15)
	v_fmac_f32_e32 v128, s30, v132
	v_fmac_f32_e32 v129, s30, v133
	v_fmac_f32_e32 v130, s30, v134
	v_fmac_f32_e32 v131, s30, v135
	global_load_dwordx4 v[132:135], v235, s[34:35] offset:0
	ds_bpermute_b32 v128, v224, v128
	ds_bpermute_b32 v129, v224, v129
	ds_bpermute_b32 v130, v224, v130
	ds_bpermute_b32 v131, v224, v131
	s_waitcnt vmcnt(15)
; __device__ __forceinline__ void epilogue(const Params& p, const Unit& u, const f32x4 (&acc)[2][2][4][2], int wr, int wc, int fr, int fq) {
;     ...
;   } else if (kind == 12) {
;     float* xo = (float*)(ws + WS_X1);
;     const int cb = u.pn * 256 + ct0;
; #pragma unroll
;     for (int ai = 0; ai < 2; ++ai)
; #pragma unroll
;       for (int mp = 0; mp < 2; ++mp) {
;         f32x4 xv[2][2][2];
; #pragma unroll
;         for (int mm = 0; mm < 2; ++mm) {
;           const int row = row0 + ai * 128 + (mp * 2 + mm) * 16;
;           const float* xr = row < TOKP ? p.in[0] + (size_t)row * 2048 : p.in[1] + (size_t)(row - TOKP) * 2048;
; #pragma unroll
;           for (int bj = 0; bj < 2; ++bj)
; #pragma unroll
;             for (int n = 0; n < 2; ++n) xv[mm][bj][n] = *(const f32x4*)(xr + cb + bj * 128 + n * 16);
;         }
; #pragma unroll
;         for (int mm = 0; mm < 2; ++mm) {
;           const int row = row0 + ai * 128 + (mp * 2 + mm) * 16;
; #pragma unroll
;           for (int bj = 0; bj < 2; ++bj)
; #pragma unroll
;             for (int n = 0; n < 2; ++n) *(f32x4*)(xo + (size_t)row * 2048 + cb + bj * 128 + n * 16) = xv[mm][bj][n] * ALPHA + acc[ai][bj][mp * 2 + mm][n];
;         }
;       }
	v_fmac_f32_e32 v124, s30, v136
	v_fmac_f32_e32 v125, s30, v137
	v_fmac_f32_e32 v126, s30, v138
	v_fmac_f32_e32 v127, s30, v139
	global_load_dwordx4 v[136:139], v235, s[34:35] offset:64
	ds_bpermute_b32 v124, v224, v124
	ds_bpermute_b32 v125, v224, v125
	ds_bpermute_b32 v126, v224, v126
	ds_bpermute_b32 v127, v224, v127
	s_waitcnt lgkmcnt(4)
	global_store_dwordx4 v225, v[128:131], s[36:37] offset:0
	s_waitcnt vmcnt(16)
	v_fmac_f32_e32 v96, s30, v140
	v_fmac_f32_e32 v97, s30, v141
	v_fmac_f32_e32 v98, s30, v142
	v_fmac_f32_e32 v99, s30, v143
	global_load_dwordx4 v[140:143], v235, s[34:35] offset:512
	ds_bpermute_b32 v96, v224, v96
	ds_bpermute_b32 v97, v224, v97
	ds_bpermute_b32 v98, v224, v98
	ds_bpermute_b32 v99, v224, v99
	s_waitcnt lgkmcnt(4)
	global_store_dwordx4 v225, v[124:127], s[36:37] offset:64
	s_waitcnt vmcnt(17)
	v_fmac_f32_e32 v92, s30, v144
	v_fmac_f32_e32 v93, s30, v145
	v_fmac_f32_e32 v94, s30, v146
	v_fmac_f32_e32 v95, s30, v147
	global_load_dwordx4 v[144:147], v235, s[34:35] offset:576
	v_add_u32_e32 v235, 0x20000, v235
	ds_bpermute_b32 v92, v224, v92
	ds_bpermute_b32 v93, v224, v93
	ds_bpermute_b32 v94, v224, v94
	ds_bpermute_b32 v95, v224, v95
	s_waitcnt lgkmcnt(4)
	global_store_dwordx4 v225, v[96:99], s[36:37] offset:512
	s_waitcnt vmcnt(18)
	v_fmac_f32_e32 v120, s30, v148
	v_fmac_f32_e32 v121, s30, v149
	v_fmac_f32_e32 v122, s30, v150
	v_fmac_f32_e32 v123, s30, v151
	global_load_dwordx4 v[148:151], v235, s[34:35] offset:0
	ds_bpermute_b32 v120, v224, v120
	ds_bpermute_b32 v121, v224, v121
	ds_bpermute_b32 v122, v224, v122
	ds_bpermute_b32 v123, v224, v123
	s_waitcnt lgkmcnt(4)
	global_store_dwordx4 v225, v[92:95], s[36:37] offset:576
	v_add_u32_e32 v225, 0x20000, v225
	s_waitcnt vmcnt(19)
	v_fmac_f32_e32 v116, s30, v152
	v_fmac_f32_e32 v117, s30, v153
	v_fmac_f32_e32 v118, s30, v154
	v_fmac_f32_e32 v119, s30, v155
	global_load_dwordx4 v[152:155], v235, s[34:35] offset:64
	ds_bpermute_b32 v116, v224, v116
	ds_bpermute_b32 v117, v224, v117
	ds_bpermute_b32 v118, v224, v118
	ds_bpermute_b32 v119, v224, v119
	s_waitcnt lgkmcnt(4)
	global_store_dwordx4 v225, v[120:123], s[36:37] offset:0
	s_waitcnt vmcnt(20)
	v_fmac_f32_e32 v88, s30, v156
	v_fmac_f32_e32 v89, s30, v157
	v_fmac_f32_e32 v90, s30, v158
	v_fmac_f32_e32 v91, s30, v159
	global_load_dwordx4 v[156:159], v235, s[34:35] offset:512
	ds_bpermute_b32 v88, v224, v88
	ds_bpermute_b32 v89, v224, v89
	ds_bpermute_b32 v90, v224, v90
	ds_bpermute_b32 v91, v224, v91
	s_waitcnt lgkmcnt(4)
	global_store_dwordx4 v225, v[116:119], s[36:37] offset:64
	s_waitcnt vmcnt(21)
	v_fmac_f32_e32 v84, s30, v160
	v_fmac_f32_e32 v85, s30, v161
	v_fmac_f32_e32 v86, s30, v162
	v_fmac_f32_e32 v87, s30, v163
	global_load_dwordx4 v[160:163], v235, s[34:35] offset:576
	v_add_u32_e32 v235, 0x20000, v235
	ds_bpermute_b32 v84, v224, v84
	ds_bpermute_b32 v85, v224, v85
	ds_bpermute_b32 v86, v224, v86
	ds_bpermute_b32 v87, v224, v87
	s_waitcnt lgkmcnt(4)
	global_store_dwordx4 v225, v[88:91], s[36:37] offset:512
	s_waitcnt vmcnt(22)
	v_fmac_f32_e32 v112, s30, v164
	v_fmac_f32_e32 v113, s30, v165
	v_fmac_f32_e32 v114, s30, v166
	v_fmac_f32_e32 v115, s30, v167
	global_load_dwordx4 v[164:167], v235, s[34:35] offset:0
	ds_bpermute_b32 v112, v224, v112
	ds_bpermute_b32 v113, v224, v113
	ds_bpermute_b32 v114, v224, v114
	ds_bpermute_b32 v115, v224, v115
	s_waitcnt lgkmcnt(4)
	global_store_dwordx4 v225, v[84:87], s[36:37] offset:576
	v_add_u32_e32 v225, 0x20000, v225
	s_waitcnt vmcnt(23)
	v_fmac_f32_e32 v108, s30, v196
	v_fmac_f32_e32 v109, s30, v197
	v_fmac_f32_e32 v110, s30, v198
	v_fmac_f32_e32 v111, s30, v199
	global_load_dwordx4 v[196:199], v235, s[34:35] offset:64
	ds_bpermute_b32 v108, v224, v108
	ds_bpermute_b32 v109, v224, v109
	ds_bpermute_b32 v110, v224, v110
	ds_bpermute_b32 v111, v224, v111
	s_waitcnt lgkmcnt(4)
	global_store_dwordx4 v225, v[112:115], s[36:37] offset:0
	s_waitcnt vmcnt(24)
	v_fmac_f32_e32 v80, s30, v200
	v_fmac_f32_e32 v81, s30, v201
	v_fmac_f32_e32 v82, s30, v202
	v_fmac_f32_e32 v83, s30, v203
	global_load_dwordx4 v[200:203], v235, s[34:35] offset:512
	ds_bpermute_b32 v80, v224, v80
	ds_bpermute_b32 v81, v224, v81
	ds_bpermute_b32 v82, v224, v82
	ds_bpermute_b32 v83, v224, v83
	s_waitcnt lgkmcnt(4)
	global_store_dwordx4 v225, v[108:111], s[36:37] offset:64
	s_waitcnt vmcnt(25)
	v_fmac_f32_e32 v76, s30, v204
	v_fmac_f32_e32 v77, s30, v205
	v_fmac_f32_e32 v78, s30, v206
	v_fmac_f32_e32 v79, s30, v207
	global_load_dwordx4 v[204:207], v235, s[34:35] offset:576
	v_add_u32_e32 v235, 0x20000, v235
	ds_bpermute_b32 v76, v224, v76
	ds_bpermute_b32 v77, v224, v77
	ds_bpermute_b32 v78, v224, v78
	ds_bpermute_b32 v79, v224, v79
	s_waitcnt lgkmcnt(4)
	global_store_dwordx4 v225, v[80:83], s[36:37] offset:512
	s_waitcnt vmcnt(26)
	v_fmac_f32_e32 v104, s30, v208
	v_fmac_f32_e32 v105, s30, v209
	v_fmac_f32_e32 v106, s30, v210
	v_fmac_f32_e32 v107, s30, v211
	global_load_dwordx4 v[208:211], v235, s[34:35] offset:0
	ds_bpermute_b32 v104, v224, v104
	ds_bpermute_b32 v105, v224, v105
	ds_bpermute_b32 v106, v224, v106
	ds_bpermute_b32 v107, v224, v107
	s_waitcnt lgkmcnt(4)
	global_store_dwordx4 v225, v[76:79], s[36:37] offset:576
	v_add_u32_e32 v225, 0x20000, v225
	s_waitcnt vmcnt(27)
	v_fmac_f32_e32 v100, s30, v212
	v_fmac_f32_e32 v101, s30, v213
	v_fmac_f32_e32 v102, s30, v214
	v_fmac_f32_e32 v103, s30, v215
	global_load_dwordx4 v[212:215], v235, s[34:35] offset:64
	ds_bpermute_b32 v100, v224, v100
	ds_bpermute_b32 v101, v224, v101
	ds_bpermute_b32 v102, v224, v102
	ds_bpermute_b32 v103, v224, v103
	s_waitcnt lgkmcnt(4)
	global_store_dwordx4 v225, v[104:107], s[36:37] offset:0
	s_waitcnt vmcnt(28)
; __device__ __forceinline__ void epilogue(const Params& p, const Unit& u, const f32x4 (&acc)[2][2][4][2], int wr, int wc, int fr, int fq) {
;     ...
;   } else if (kind == 12) {
;     float* xo = (float*)(ws + WS_X1);
;     const int cb = u.pn * 256 + ct0;
; #pragma unroll
;     for (int ai = 0; ai < 2; ++ai)
; #pragma unroll
;       for (int mp = 0; mp < 2; ++mp) {
;         f32x4 xv[2][2][2];
; #pragma unroll
;         for (int mm = 0; mm < 2; ++mm) {
;           const int row = row0 + ai * 128 + (mp * 2 + mm) * 16;
;           const float* xr = row < TOKP ? p.in[0] + (size_t)row * 2048 : p.in[1] + (size_t)(row - TOKP) * 2048;
; #pragma unroll
;           for (int bj = 0; bj < 2; ++bj)
; #pragma unroll
;             for (int n = 0; n < 2; ++n) xv[mm][bj][n] = *(const f32x4*)(xr + cb + bj * 128 + n * 16);
;         }
; #pragma unroll
;         for (int mm = 0; mm < 2; ++mm) {
;           const int row = row0 + ai * 128 + (mp * 2 + mm) * 16;
; #pragma unroll
;           for (int bj = 0; bj < 2; ++bj)
; #pragma unroll
;             for (int n = 0; n < 2; ++n) *(f32x4*)(xo + (size_t)row * 2048 + cb + bj * 128 + n * 16) = xv[mm][bj][n] * ALPHA + acc[ai][bj][mp * 2 + mm][n];
;         }
;       }
	v_fmac_f32_e32 v72, s30, v216
	v_fmac_f32_e32 v73, s30, v217
	v_fmac_f32_e32 v74, s30, v218
	v_fmac_f32_e32 v75, s30, v219
	global_load_dwordx4 v[216:219], v235, s[34:35] offset:512
	ds_bpermute_b32 v72, v224, v72
	ds_bpermute_b32 v73, v224, v73
	ds_bpermute_b32 v74, v224, v74
	ds_bpermute_b32 v75, v224, v75
	s_waitcnt lgkmcnt(4)
	global_store_dwordx4 v225, v[100:103], s[36:37] offset:64
	s_waitcnt vmcnt(29)
	v_fmac_f32_e32 v68, s30, v220
	v_fmac_f32_e32 v69, s30, v221
	v_fmac_f32_e32 v70, s30, v222
	v_fmac_f32_e32 v71, s30, v223
	global_load_dwordx4 v[220:223], v235, s[34:35] offset:576
	ds_bpermute_b32 v68, v224, v68
	ds_bpermute_b32 v69, v224, v69
	ds_bpermute_b32 v70, v224, v70
	ds_bpermute_b32 v71, v224, v71
	s_waitcnt lgkmcnt(4)
	global_store_dwordx4 v225, v[72:75], s[36:37] offset:512
	s_waitcnt vmcnt(30)
	v_fmac_f32_e32 v60, s30, v132
	v_fmac_f32_e32 v61, s30, v133
	v_fmac_f32_e32 v62, s30, v134
	v_fmac_f32_e32 v63, s30, v135
	ds_bpermute_b32 v60, v224, v60
	ds_bpermute_b32 v61, v224, v61
	ds_bpermute_b32 v62, v224, v62
	ds_bpermute_b32 v63, v224, v63
	s_waitcnt lgkmcnt(4)
	global_store_dwordx4 v225, v[68:71], s[36:37] offset:576
	v_add_u32_e32 v225, 0xa0000, v225
	s_waitcnt vmcnt(30)
	v_fmac_f32_e32 v56, s30, v136
	v_fmac_f32_e32 v57, s30, v137
	v_fmac_f32_e32 v58, s30, v138
	v_fmac_f32_e32 v59, s30, v139
	ds_bpermute_b32 v56, v224, v56
	ds_bpermute_b32 v57, v224, v57
	ds_bpermute_b32 v58, v224, v58
	ds_bpermute_b32 v59, v224, v59
	s_waitcnt lgkmcnt(4)
	global_store_dwordx4 v225, v[60:63], s[36:37] offset:0
	s_waitcnt vmcnt(29)
	v_fmac_f32_e32 v28, s30, v140
	v_fmac_f32_e32 v29, s30, v141
	v_fmac_f32_e32 v30, s30, v142
	v_fmac_f32_e32 v31, s30, v143
	ds_bpermute_b32 v28, v224, v28
	ds_bpermute_b32 v29, v224, v29
	ds_bpermute_b32 v30, v224, v30
	ds_bpermute_b32 v31, v224, v31
	s_waitcnt lgkmcnt(4)
	global_store_dwordx4 v225, v[56:59], s[36:37] offset:64
	s_waitcnt vmcnt(28)
	v_fmac_f32_e32 v24, s30, v144
	v_fmac_f32_e32 v25, s30, v145
	v_fmac_f32_e32 v26, s30, v146
	v_fmac_f32_e32 v27, s30, v147
	ds_bpermute_b32 v24, v224, v24
	ds_bpermute_b32 v25, v224, v25
	ds_bpermute_b32 v26, v224, v26
	ds_bpermute_b32 v27, v224, v27
	s_waitcnt lgkmcnt(4)
	global_store_dwordx4 v225, v[28:31], s[36:37] offset:512
	s_waitcnt vmcnt(27)
	v_fmac_f32_e32 v52, s30, v148
	v_fmac_f32_e32 v53, s30, v149
	v_fmac_f32_e32 v54, s30, v150
	v_fmac_f32_e32 v55, s30, v151
	ds_bpermute_b32 v52, v224, v52
	ds_bpermute_b32 v53, v224, v53
	ds_bpermute_b32 v54, v224, v54
	ds_bpermute_b32 v55, v224, v55
	s_waitcnt lgkmcnt(4)
	global_store_dwordx4 v225, v[24:27], s[36:37] offset:576
	v_add_u32_e32 v225, 0x20000, v225
	s_waitcnt vmcnt(26)
	v_fmac_f32_e32 v48, s30, v152
	v_fmac_f32_e32 v49, s30, v153
	v_fmac_f32_e32 v50, s30, v154
	v_fmac_f32_e32 v51, s30, v155
	ds_bpermute_b32 v48, v224, v48
	ds_bpermute_b32 v49, v224, v49
	ds_bpermute_b32 v50, v224, v50
	ds_bpermute_b32 v51, v224, v51
	s_waitcnt lgkmcnt(4)
	global_store_dwordx4 v225, v[52:55], s[36:37] offset:0
	s_waitcnt vmcnt(25)
	v_fmac_f32_e32 v20, s30, v156
	v_fmac_f32_e32 v21, s30, v157
	v_fmac_f32_e32 v22, s30, v158
	v_fmac_f32_e32 v23, s30, v159
	ds_bpermute_b32 v20, v224, v20
	ds_bpermute_b32 v21, v224, v21
	ds_bpermute_b32 v22, v224, v22
	ds_bpermute_b32 v23, v224, v23
	s_waitcnt lgkmcnt(4)
	global_store_dwordx4 v225, v[48:51], s[36:37] offset:64
	s_waitcnt vmcnt(24)
	v_fmac_f32_e32 v16, s30, v160
	v_fmac_f32_e32 v17, s30, v161
	v_fmac_f32_e32 v18, s30, v162
	v_fmac_f32_e32 v19, s30, v163
	ds_bpermute_b32 v16, v224, v16
	ds_bpermute_b32 v17, v224, v17
	ds_bpermute_b32 v18, v224, v18
	ds_bpermute_b32 v19, v224, v19
	s_waitcnt lgkmcnt(4)
	global_store_dwordx4 v225, v[20:23], s[36:37] offset:512
	s_waitcnt vmcnt(23)
	v_fmac_f32_e32 v44, s30, v164
	v_fmac_f32_e32 v45, s30, v165
	v_fmac_f32_e32 v46, s30, v166
	v_fmac_f32_e32 v47, s30, v167
	ds_bpermute_b32 v44, v224, v44
	ds_bpermute_b32 v45, v224, v45
	ds_bpermute_b32 v46, v224, v46
	ds_bpermute_b32 v47, v224, v47
	s_waitcnt lgkmcnt(4)
	global_store_dwordx4 v225, v[16:19], s[36:37] offset:576
	v_add_u32_e32 v225, 0x20000, v225
	s_waitcnt vmcnt(22)
	v_fmac_f32_e32 v40, s30, v196
	v_fmac_f32_e32 v41, s30, v197
	v_fmac_f32_e32 v42, s30, v198
	v_fmac_f32_e32 v43, s30, v199
	ds_bpermute_b32 v40, v224, v40
	ds_bpermute_b32 v41, v224, v41
	ds_bpermute_b32 v42, v224, v42
	ds_bpermute_b32 v43, v224, v43
	s_waitcnt lgkmcnt(4)
	global_store_dwordx4 v225, v[44:47], s[36:37] offset:0
	s_waitcnt vmcnt(21)
	v_fmac_f32_e32 v12, s30, v200
	v_fmac_f32_e32 v13, s30, v201
	v_fmac_f32_e32 v14, s30, v202
	v_fmac_f32_e32 v15, s30, v203
	ds_bpermute_b32 v12, v224, v12
	ds_bpermute_b32 v13, v224, v13
	ds_bpermute_b32 v14, v224, v14
	ds_bpermute_b32 v15, v224, v15
	s_waitcnt lgkmcnt(4)
	global_store_dwordx4 v225, v[40:43], s[36:37] offset:64
	s_waitcnt vmcnt(20)
	v_fmac_f32_e32 v8, s30, v204
	v_fmac_f32_e32 v9, s30, v205
	v_fmac_f32_e32 v10, s30, v206
	v_fmac_f32_e32 v11, s30, v207
	ds_bpermute_b32 v8, v224, v8
	ds_bpermute_b32 v9, v224, v9
	ds_bpermute_b32 v10, v224, v10
	ds_bpermute_b32 v11, v224, v11
	s_waitcnt lgkmcnt(4)
	global_store_dwordx4 v225, v[12:15], s[36:37] offset:512
	s_waitcnt vmcnt(19)
	v_fmac_f32_e32 v36, s30, v208
	v_fmac_f32_e32 v37, s30, v209
	v_fmac_f32_e32 v38, s30, v210
	v_fmac_f32_e32 v39, s30, v211
	ds_bpermute_b32 v36, v224, v36
	ds_bpermute_b32 v37, v224, v37
	ds_bpermute_b32 v38, v224, v38
	ds_bpermute_b32 v39, v224, v39
	s_waitcnt lgkmcnt(4)
	global_store_dwordx4 v225, v[8:11], s[36:37] offset:576
	v_add_u32_e32 v225, 0x20000, v225
	s_waitcnt vmcnt(18)
	v_fmac_f32_e32 v32, s30, v212
	v_fmac_f32_e32 v33, s30, v213
	v_fmac_f32_e32 v34, s30, v214
	v_fmac_f32_e32 v35, s30, v215
	ds_bpermute_b32 v32, v224, v32
	ds_bpermute_b32 v33, v224, v33
	ds_bpermute_b32 v34, v224, v34
	ds_bpermute_b32 v35, v224, v35
	s_waitcnt lgkmcnt(4)
	global_store_dwordx4 v225, v[36:39], s[36:37] offset:0
	s_waitcnt vmcnt(17)
	v_fmac_f32_e32 v4, s30, v216
	v_fmac_f32_e32 v5, s30, v217
	v_fmac_f32_e32 v6, s30, v218
	v_fmac_f32_e32 v7, s30, v219
	ds_bpermute_b32 v4, v224, v4
	ds_bpermute_b32 v5, v224, v5
	ds_bpermute_b32 v6, v224, v6
	ds_bpermute_b32 v7, v224, v7
	s_waitcnt lgkmcnt(4)
	global_store_dwordx4 v225, v[32:35], s[36:37] offset:64
	s_waitcnt vmcnt(16)
	v_fmac_f32_e32 v0, s30, v220
	v_fmac_f32_e32 v1, s30, v221
	v_fmac_f32_e32 v2, s30, v222
	v_fmac_f32_e32 v3, s30, v223
	ds_bpermute_b32 v0, v224, v0
	ds_bpermute_b32 v1, v224, v1
	ds_bpermute_b32 v2, v224, v2
	ds_bpermute_b32 v3, v224, v3
	s_waitcnt lgkmcnt(4)
	global_store_dwordx4 v225, v[4:7], s[36:37] offset:512
	s_waitcnt lgkmcnt(0)
	global_store_dwordx4 v225, v[0:3], s[36:37] offset:576
	s_branch .LBB0_987

; __device__ __forceinline__ void epilogue(const Params& p, const Unit& u, const f32x4 (&acc)[2][2][4][2], int wr, int wc, int fr, int fq) {
;     ...
;   } else if (kind == 12) {
;     float* xo = (float*)(ws + WS_X1);
;     const int cb = u.pn * 256 + ct0;
; #pragma unroll
;     for (int ai = 0; ai < 2; ++ai)
; #pragma unroll
;       for (int mp = 0; mp < 2; ++mp) {
;         f32x4 xv[2][2][2];
; #pragma unroll
;         for (int mm = 0; mm < 2; ++mm) {
;           const int row = row0 + ai * 128 + (mp * 2 + mm) * 16;
;           const float* xr = row < TOKP ? p.in[0] + (size_t)row * 2048 : p.in[1] + (size_t)(row - TOKP) * 2048;
; #pragma unroll
;           for (int bj = 0; bj < 2; ++bj)
; #pragma unroll
;             for (int n = 0; n < 2; ++n) xv[mm][bj][n] = *(const f32x4*)(xr + cb + bj * 128 + n * 16);
;         }
; #pragma unroll
;         for (int mm = 0; mm < 2; ++mm) {
;           const int row = row0 + ai * 128 + (mp * 2 + mm) * 16;
; #pragma unroll
;           for (int bj = 0; bj < 2; ++bj)
; #pragma unroll
;             for (int n = 0; n < 2; ++n) *(f32x4*)(xo + (size_t)row * 2048 + cb + bj * 128 + n * 16) = xv[mm][bj][n] * ALPHA + acc[ai][bj][mp * 2 + mm][n];
;         }
;       }
.LBB0_777:
	s_branch .Le12_ep
	s_movk_i32 s29, 0x2000
	v_add_u32_e32 v64, 0xffffe000, v66
	v_cmp_gt_i32_e32 vcc, s29, v66
	v_ashrrev_i32_e32 v67, 31, v66
	v_mov_b32_e32 v134, s5
	v_cndmask_b32_e32 v132, v64, v66, vcc
	v_mov_b32_e32 v64, s7
	v_cndmask_b32_e32 v133, 0, v67, vcc
	v_cndmask_b32_e32 v135, v64, v134, vcc
	v_mov_b32_e32 v64, s6
	v_mov_b32_e32 v134, s4
	v_lshl_or_b32 v148, s78, 8, v174
	v_cndmask_b32_e32 v134, v64, v134, vcc
	v_lshlrev_b64 v[132:133], 13, v[132:133]
	v_ashrrev_i32_e32 v149, 31, v148
	v_lshl_add_u64 v[132:133], v[134:135], 0, v[132:133]
	v_lshl_add_u64 v[132:133], v[148:149], 2, v[132:133]
	global_load_dwordx4 v[144:147], v[132:133], off
	global_load_dwordx4 v[140:143], v[132:133], off offset:64
	global_load_dwordx4 v[136:139], v[132:133], off offset:512
	s_nop 0
	global_load_dwordx4 v[132:135], v[132:133], off offset:576
	v_or_b32_e32 v150, 16, v66
	s_movk_i32 s29, 0x1fff
	v_cmp_lt_i32_e32 vcc, s29, v150
	s_and_saveexec_b64 s[34:35], vcc
	s_xor_b64 s[36:37], exec, s[34:35]
	v_add_u32_e32 v64, 0xffffe010, v66
	v_lshlrev_b64 v[152:153], 13, v[64:65]
	v_mov_b32_e32 v151, v65
	v_lshl_add_u64 v[154:155], s[6:7], 0, v[152:153]
	v_lshlrev_b64 v[152:153], 13, v[150:151]
	s_andn2_saveexec_b64 s[36:37], s[36:37]
	v_ashrrev_i32_e32 v151, 31, v150
	v_lshlrev_b64 v[152:153], 13, v[150:151]
	v_lshl_add_u64 v[154:155], s[4:5], 0, v[152:153]
	s_or_b64 exec, exec, s[36:37]
	v_lshlrev_b64 v[150:151], 2, v[148:149]
	v_lshl_add_u64 v[166:167], v[154:155], 0, v[150:151]
	global_load_dwordx4 v[154:157], v[166:167], off
	global_load_dwordx4 v[158:161], v[166:167], off offset:64
	global_load_dwordx4 v[162:165], v[166:167], off offset:512
	global_load_dwordx4 v[196:199], v[166:167], off offset:576
	v_readlane_b32 s34, v254, 30
	v_readlane_b32 s35, v254, 31
	v_lshlrev_b64 v[166:167], 13, v[66:67]
	s_waitcnt vmcnt(0)
	v_pk_fma_f32 v[138:139], v[138:139], s[2:3], v[98:99] op_sel_hi:[1,0,1]
	v_lshl_add_u64 v[148:149], s[34:35], 0, v[150:151]
	v_lshl_add_u64 v[166:167], v[148:149], 0, v[166:167]
	v_pk_fma_f32 v[136:137], v[136:137], s[2:3], v[96:97] op_sel_hi:[1,0,1]
	v_pk_fma_f32 v[134:135], v[134:135], s[2:3], v[94:95] op_sel_hi:[1,0,1]
	v_pk_fma_f32 v[132:133], v[132:133], s[2:3], v[92:93] op_sel_hi:[1,0,1]
	v_pk_fma_f32 v[146:147], v[146:147], s[2:3], v[130:131] op_sel_hi:[1,0,1]
	v_pk_fma_f32 v[144:145], v[144:145], s[2:3], v[128:129] op_sel_hi:[1,0,1]
	v_pk_fma_f32 v[142:143], v[142:143], s[2:3], v[126:127] op_sel_hi:[1,0,1]
	v_pk_fma_f32 v[140:141], v[140:141], s[2:3], v[124:125] op_sel_hi:[1,0,1]
	global_store_dwordx4 v[166:167], v[136:139], off offset:512
	global_store_dwordx4 v[166:167], v[132:135], off offset:576
	global_store_dwordx4 v[166:167], v[144:147], off
	v_lshl_add_u64 v[136:137], v[148:149], 0, v[152:153]
	global_store_dwordx4 v[166:167], v[140:143], off offset:64
	s_movk_i32 s29, 0x2000
	v_add_u32_e32 v64, 0xffffe020, v66
	v_mov_b32_e32 v67, s5
	v_mov_b32_e32 v200, s6
	v_mov_b32_e32 v201, s4
	v_add_u32_e32 v152, 0xffffe030, v66
	v_pk_fma_f32 v[132:133], v[154:155], s[2:3], v[120:121] op_sel_hi:[1,0,1]
	v_pk_fma_f32 v[134:135], v[156:157], s[2:3], v[122:123] op_sel_hi:[1,0,1]
	global_store_dwordx4 v[136:137], v[132:135], off
	s_nop 1
	v_pk_fma_f32 v[132:133], v[158:159], s[2:3], v[116:117] op_sel_hi:[1,0,1]
	v_pk_fma_f32 v[134:135], v[160:161], s[2:3], v[118:119] op_sel_hi:[1,0,1]
	global_store_dwordx4 v[136:137], v[132:135], off offset:64
	s_nop 1
	v_pk_fma_f32 v[132:133], v[162:163], s[2:3], v[88:89] op_sel_hi:[1,0,1]
	v_pk_fma_f32 v[134:135], v[164:165], s[2:3], v[90:91] op_sel_hi:[1,0,1]
	global_store_dwordx4 v[136:137], v[132:135], off offset:512
	s_nop 1
	v_pk_fma_f32 v[132:133], v[196:197], s[2:3], v[84:85] op_sel_hi:[1,0,1]
	v_or_b32_e32 v196, 32, v66
	v_pk_fma_f32 v[134:135], v[198:199], s[2:3], v[86:87] op_sel_hi:[1,0,1]
	v_cmp_gt_i32_e32 vcc, s29, v196
	v_ashrrev_i32_e32 v197, 31, v196
	global_store_dwordx4 v[136:137], v[132:135], off offset:576
	v_or_b32_e32 v198, 48, v66
	v_ashrrev_i32_e32 v199, 31, v198
	v_cndmask_b32_e32 v133, 0, v197, vcc
	v_cndmask_b32_e32 v132, v64, v196, vcc
	v_mov_b32_e32 v64, s7
	v_cndmask_b32_e32 v135, v64, v67, vcc
	v_cndmask_b32_e32 v134, v200, v201, vcc
	v_lshlrev_b64 v[132:133], 13, v[132:133]
	v_lshl_add_u64 v[132:133], v[134:135], 0, v[132:133]
	v_lshl_add_u64 v[144:145], v[132:133], 0, v[150:151]
	global_load_dwordx4 v[132:135], v[144:145], off
	global_load_dwordx4 v[136:139], v[144:145], off offset:64
	global_load_dwordx4 v[140:143], v[144:145], off offset:512
	s_nop 0
	global_load_dwordx4 v[144:147], v[144:145], off offset:576
	v_cmp_gt_i32_e32 vcc, s29, v198
	v_lshlrev_b64 v[196:197], 13, v[196:197]
	v_lshl_add_u64 v[196:197], v[148:149], 0, v[196:197]
	v_cndmask_b32_e32 v153, 0, v199, vcc
	v_cndmask_b32_e32 v152, v152, v198, vcc
	v_cndmask_b32_e32 v155, v64, v67, vcc
	v_cndmask_b32_e32 v154, v200, v201, vcc
	v_lshlrev_b64 v[152:153], 13, v[152:153]
	v_lshl_add_u64 v[152:153], v[154:155], 0, v[152:153]
	v_lshl_add_u64 v[164:165], v[152:153], 0, v[150:151]
	global_load_dwordx4 v[152:155], v[164:165], off
	global_load_dwordx4 v[156:159], v[164:165], off offset:64
	global_load_dwordx4 v[160:163], v[164:165], off offset:512
	s_nop 0
	global_load_dwordx4 v[164:167], v[164:165], off offset:576
	s_movk_i32 s29, 0x1f80
	v_cmp_gt_i32_e32 vcc, s29, v66
	s_movk_i32 s29, 0x1f6f
	s_waitcnt vmcnt(0)
; __device__ __forceinline__ void epilogue(const Params& p, const Unit& u, const f32x4 (&acc)[2][2][4][2], int wr, int wc, int fr, int fq) {
;     ...
;   } else if (kind == 12) {
;     float* xo = (float*)(ws + WS_X1);
;     const int cb = u.pn * 256 + ct0;
; #pragma unroll
;     for (int ai = 0; ai < 2; ++ai)
; #pragma unroll
;       for (int mp = 0; mp < 2; ++mp) {
;         f32x4 xv[2][2][2];
; #pragma unroll
;         for (int mm = 0; mm < 2; ++mm) {
;           const int row = row0 + ai * 128 + (mp * 2 + mm) * 16;
;           const float* xr = row < TOKP ? p.in[0] + (size_t)row * 2048 : p.in[1] + (size_t)(row - TOKP) * 2048;
; #pragma unroll
;           for (int bj = 0; bj < 2; ++bj)
; #pragma unroll
;             for (int n = 0; n < 2; ++n) xv[mm][bj][n] = *(const f32x4*)(xr + cb + bj * 128 + n * 16);
;         }
; #pragma unroll
;         for (int mm = 0; mm < 2; ++mm) {
;           const int row = row0 + ai * 128 + (mp * 2 + mm) * 16;
; #pragma unroll
;           for (int bj = 0; bj < 2; ++bj)
; #pragma unroll
;             for (int n = 0; n < 2; ++n) *(f32x4*)(xo + (size_t)row * 2048 + cb + bj * 128 + n * 16) = xv[mm][bj][n] * ALPHA + acc[ai][bj][mp * 2 + mm][n];
;         }
;       }
	v_pk_fma_f32 v[134:135], v[134:135], s[2:3], v[114:115] op_sel_hi:[1,0,1]
	v_pk_fma_f32 v[132:133], v[132:133], s[2:3], v[112:113] op_sel_hi:[1,0,1]
	global_store_dwordx4 v[196:197], v[132:135], off
	s_nop 1
	v_pk_fma_f32 v[134:135], v[138:139], s[2:3], v[110:111] op_sel_hi:[1,0,1]
	v_pk_fma_f32 v[132:133], v[136:137], s[2:3], v[108:109] op_sel_hi:[1,0,1]
	global_store_dwordx4 v[196:197], v[132:135], off offset:64
	s_nop 1
	v_pk_fma_f32 v[134:135], v[142:143], s[2:3], v[82:83] op_sel_hi:[1,0,1]
	v_pk_fma_f32 v[132:133], v[140:141], s[2:3], v[80:81] op_sel_hi:[1,0,1]
	global_store_dwordx4 v[196:197], v[132:135], off offset:512
	s_nop 1
	v_pk_fma_f32 v[134:135], v[146:147], s[2:3], v[78:79] op_sel_hi:[1,0,1]
	v_pk_fma_f32 v[132:133], v[144:145], s[2:3], v[76:77] op_sel_hi:[1,0,1]
	global_store_dwordx4 v[196:197], v[132:135], off offset:576
	s_nop 1
	v_lshlrev_b64 v[132:133], 13, v[198:199]
	v_lshl_add_u64 v[136:137], v[148:149], 0, v[132:133]
	v_pk_fma_f32 v[134:135], v[154:155], s[2:3], v[106:107] op_sel_hi:[1,0,1]
	v_pk_fma_f32 v[132:133], v[152:153], s[2:3], v[104:105] op_sel_hi:[1,0,1]
	global_store_dwordx4 v[136:137], v[132:135], off
	v_add_u32_e32 v152, 0x80, v66
	v_ashrrev_i32_e32 v153, 31, v152
	v_pk_fma_f32 v[134:135], v[158:159], s[2:3], v[102:103] op_sel_hi:[1,0,1]
	v_pk_fma_f32 v[132:133], v[156:157], s[2:3], v[100:101] op_sel_hi:[1,0,1]
	global_store_dwordx4 v[136:137], v[132:135], off offset:64
	v_add_u32_e32 v156, 0x90, v66
	s_nop 0
	v_pk_fma_f32 v[134:135], v[162:163], s[2:3], v[74:75] op_sel_hi:[1,0,1]
	v_pk_fma_f32 v[132:133], v[160:161], s[2:3], v[72:73] op_sel_hi:[1,0,1]
	global_store_dwordx4 v[136:137], v[132:135], off offset:512
	s_nop 1
	v_pk_fma_f32 v[134:135], v[166:167], s[2:3], v[70:71] op_sel_hi:[1,0,1]
	v_pk_fma_f32 v[132:133], v[164:165], s[2:3], v[68:69] op_sel_hi:[1,0,1]
	global_store_dwordx4 v[136:137], v[132:135], off offset:576
	s_nop 1
	v_add_u32_e32 v132, 0xffffe080, v66
	v_cndmask_b32_e32 v133, 0, v153, vcc
	v_cndmask_b32_e32 v132, v132, v152, vcc
	v_cndmask_b32_e32 v135, v64, v67, vcc
	v_cndmask_b32_e32 v134, v200, v201, vcc
	v_lshlrev_b64 v[132:133], 13, v[132:133]
	v_lshl_add_u64 v[132:133], v[134:135], 0, v[132:133]
	v_lshl_add_u64 v[132:133], v[132:133], 0, v[150:151]
	global_load_dwordx4 v[144:147], v[132:133], off
	global_load_dwordx4 v[140:143], v[132:133], off offset:64
	global_load_dwordx4 v[136:139], v[132:133], off offset:512
	s_nop 0
	global_load_dwordx4 v[132:135], v[132:133], off offset:576
	v_cmp_lt_i32_e32 vcc, s29, v66
	s_and_saveexec_b64 s[34:35], vcc
	s_xor_b64 s[36:37], exec, s[34:35]
	v_add_u32_e32 v64, 0xffffe090, v66
	v_lshlrev_b64 v[154:155], 13, v[64:65]
	v_mov_b32_e32 v157, v65
	v_lshl_add_u64 v[158:159], s[6:7], 0, v[154:155]
	v_lshlrev_b64 v[154:155], 13, v[156:157]
	s_andn2_saveexec_b64 s[36:37], s[36:37]
	v_ashrrev_i32_e32 v157, 31, v156
	v_lshlrev_b64 v[154:155], 13, v[156:157]
	v_lshl_add_u64 v[158:159], s[4:5], 0, v[154:155]
	s_or_b64 exec, exec, s[36:37]
	v_lshl_add_u64 v[196:197], v[158:159], 0, v[150:151]
	global_load_dwordx4 v[156:159], v[196:197], off
	global_load_dwordx4 v[160:163], v[196:197], off offset:64
	global_load_dwordx4 v[164:167], v[196:197], off offset:512
	s_nop 0
	global_load_dwordx4 v[196:199], v[196:197], off offset:576
	v_lshlrev_b64 v[152:153], 13, v[152:153]
	v_lshl_add_u64 v[152:153], v[148:149], 0, v[152:153]
	s_waitcnt vmcnt(0)
; __device__ __forceinline__ void epilogue(const Params& p, const Unit& u, const f32x4 (&acc)[2][2][4][2], int wr, int wc, int fr, int fq) {
;     ...
;   } else if (kind == 12) {
;     float* xo = (float*)(ws + WS_X1);
;     const int cb = u.pn * 256 + ct0;
; #pragma unroll
;     for (int ai = 0; ai < 2; ++ai)
; #pragma unroll
;       for (int mp = 0; mp < 2; ++mp) {
;         f32x4 xv[2][2][2];
; #pragma unroll
;         for (int mm = 0; mm < 2; ++mm) {
;           const int row = row0 + ai * 128 + (mp * 2 + mm) * 16;
;           const float* xr = row < TOKP ? p.in[0] + (size_t)row * 2048 : p.in[1] + (size_t)(row - TOKP) * 2048;
; #pragma unroll
;           for (int bj = 0; bj < 2; ++bj)
; #pragma unroll
;             for (int n = 0; n < 2; ++n) xv[mm][bj][n] = *(const f32x4*)(xr + cb + bj * 128 + n * 16);
;         }
; #pragma unroll
;         for (int mm = 0; mm < 2; ++mm) {
;           const int row = row0 + ai * 128 + (mp * 2 + mm) * 16;
; #pragma unroll
;           for (int bj = 0; bj < 2; ++bj)
; #pragma unroll
;             for (int n = 0; n < 2; ++n) *(f32x4*)(xo + (size_t)row * 2048 + cb + bj * 128 + n * 16) = xv[mm][bj][n] * ALPHA + acc[ai][bj][mp * 2 + mm][n];
;         }
;       }
	v_pk_fma_f32 v[138:139], v[138:139], s[2:3], v[30:31] op_sel_hi:[1,0,1]
	v_pk_fma_f32 v[136:137], v[136:137], s[2:3], v[28:29] op_sel_hi:[1,0,1]
	v_pk_fma_f32 v[134:135], v[134:135], s[2:3], v[26:27] op_sel_hi:[1,0,1]
	v_pk_fma_f32 v[132:133], v[132:133], s[2:3], v[24:25] op_sel_hi:[1,0,1]
	v_pk_fma_f32 v[146:147], v[146:147], s[2:3], v[62:63] op_sel_hi:[1,0,1]
	v_pk_fma_f32 v[144:145], v[144:145], s[2:3], v[60:61] op_sel_hi:[1,0,1]
	v_pk_fma_f32 v[142:143], v[142:143], s[2:3], v[58:59] op_sel_hi:[1,0,1]
	v_pk_fma_f32 v[140:141], v[140:141], s[2:3], v[56:57] op_sel_hi:[1,0,1]
	global_store_dwordx4 v[152:153], v[136:139], off offset:512
	global_store_dwordx4 v[152:153], v[132:135], off offset:576
	global_store_dwordx4 v[152:153], v[144:147], off
	v_lshl_add_u64 v[136:137], v[148:149], 0, v[154:155]
	global_store_dwordx4 v[152:153], v[140:143], off offset:64
	s_movk_i32 s29, 0x1f60
	v_cmp_gt_i32_e32 vcc, s29, v66
	v_add_u32_e32 v64, 0xffffe0a0, v66
	v_mov_b32_e32 v67, s5
	v_mov_b32_e32 v154, s6
	s_movk_i32 s29, 0x1f50
	v_add_u32_e32 v152, 0xffffe0b0, v66
	v_pk_fma_f32 v[132:133], v[156:157], s[2:3], v[52:53] op_sel_hi:[1,0,1]
	v_pk_fma_f32 v[134:135], v[158:159], s[2:3], v[54:55] op_sel_hi:[1,0,1]
	global_store_dwordx4 v[136:137], v[132:135], off
	v_mov_b32_e32 v156, s4
	s_nop 0
	v_pk_fma_f32 v[132:133], v[160:161], s[2:3], v[48:49] op_sel_hi:[1,0,1]
	v_pk_fma_f32 v[134:135], v[162:163], s[2:3], v[50:51] op_sel_hi:[1,0,1]
	global_store_dwordx4 v[136:137], v[132:135], off offset:64
	s_nop 1
	v_pk_fma_f32 v[132:133], v[164:165], s[2:3], v[20:21] op_sel_hi:[1,0,1]
	v_pk_fma_f32 v[134:135], v[166:167], s[2:3], v[22:23] op_sel_hi:[1,0,1]
	v_add_u32_e32 v166, 0xa0, v66
	global_store_dwordx4 v[136:137], v[132:135], off offset:512
	v_ashrrev_i32_e32 v167, 31, v166
	s_nop 0
	v_pk_fma_f32 v[132:133], v[196:197], s[2:3], v[16:17] op_sel_hi:[1,0,1]
	v_pk_fma_f32 v[134:135], v[198:199], s[2:3], v[18:19] op_sel_hi:[1,0,1]
	global_store_dwordx4 v[136:137], v[132:135], off offset:576
	v_add_u32_e32 v196, 0xb0, v66
	v_ashrrev_i32_e32 v197, 31, v196
	v_cndmask_b32_e32 v133, 0, v167, vcc
	v_cndmask_b32_e32 v132, v64, v166, vcc
	v_mov_b32_e32 v64, s7
	v_cndmask_b32_e32 v135, v64, v67, vcc
	v_cndmask_b32_e32 v134, v154, v156, vcc
	v_lshlrev_b64 v[132:133], 13, v[132:133]
	v_lshl_add_u64 v[132:133], v[134:135], 0, v[132:133]
	v_lshl_add_u64 v[144:145], v[132:133], 0, v[150:151]
	global_load_dwordx4 v[132:135], v[144:145], off
	global_load_dwordx4 v[136:139], v[144:145], off offset:64
	global_load_dwordx4 v[140:143], v[144:145], off offset:512
	s_nop 0
	global_load_dwordx4 v[144:147], v[144:145], off offset:576
	v_cmp_gt_i32_e32 vcc, s29, v66
	v_lshlrev_b64 v[166:167], 13, v[166:167]
	v_lshl_add_u64 v[166:167], v[148:149], 0, v[166:167]
	v_cndmask_b32_e32 v153, 0, v197, vcc
	v_cndmask_b32_e32 v152, v152, v196, vcc
	v_cndmask_b32_e32 v155, v64, v67, vcc
	v_cndmask_b32_e32 v154, v154, v156, vcc
	v_lshlrev_b64 v[152:153], 13, v[152:153]
	v_lshl_add_u64 v[152:153], v[154:155], 0, v[152:153]
	v_lshl_add_u64 v[162:163], v[152:153], 0, v[150:151]
	global_load_dwordx4 v[150:153], v[162:163], off
	global_load_dwordx4 v[154:157], v[162:163], off offset:64
	global_load_dwordx4 v[158:161], v[162:163], off offset:512
	s_nop 0
	global_load_dwordx4 v[162:165], v[162:163], off offset:576
	s_waitcnt vmcnt(0)
	v_pk_fma_f32 v[134:135], v[134:135], s[2:3], v[46:47] op_sel_hi:[1,0,1]
	v_pk_fma_f32 v[132:133], v[132:133], s[2:3], v[44:45] op_sel_hi:[1,0,1]
	global_store_dwordx4 v[166:167], v[132:135], off
	s_nop 1
	v_pk_fma_f32 v[134:135], v[138:139], s[2:3], v[42:43] op_sel_hi:[1,0,1]
	v_pk_fma_f32 v[132:133], v[136:137], s[2:3], v[40:41] op_sel_hi:[1,0,1]
	global_store_dwordx4 v[166:167], v[132:135], off offset:64
	s_nop 1
	v_pk_fma_f32 v[134:135], v[142:143], s[2:3], v[14:15] op_sel_hi:[1,0,1]
	v_pk_fma_f32 v[132:133], v[140:141], s[2:3], v[12:13] op_sel_hi:[1,0,1]
	global_store_dwordx4 v[166:167], v[132:135], off offset:512
	s_nop 1
	v_pk_fma_f32 v[134:135], v[146:147], s[2:3], v[10:11] op_sel_hi:[1,0,1]
	v_pk_fma_f32 v[132:133], v[144:145], s[2:3], v[8:9] op_sel_hi:[1,0,1]
	global_store_dwordx4 v[166:167], v[132:135], off offset:576
	s_nop 1
	v_lshlrev_b64 v[132:133], 13, v[196:197]
	v_lshl_add_u64 v[136:137], v[148:149], 0, v[132:133]
	v_pk_fma_f32 v[134:135], v[152:153], s[2:3], v[38:39] op_sel_hi:[1,0,1]
	v_pk_fma_f32 v[132:133], v[150:151], s[2:3], v[36:37] op_sel_hi:[1,0,1]
	global_store_dwordx4 v[136:137], v[132:135], off
	s_nop 1
	v_pk_fma_f32 v[134:135], v[156:157], s[2:3], v[34:35] op_sel_hi:[1,0,1]
	v_pk_fma_f32 v[132:133], v[154:155], s[2:3], v[32:33] op_sel_hi:[1,0,1]
	global_store_dwordx4 v[136:137], v[132:135], off offset:64
	s_nop 1
	v_pk_fma_f32 v[134:135], v[160:161], s[2:3], v[6:7] op_sel_hi:[1,0,1]
	v_pk_fma_f32 v[132:133], v[158:159], s[2:3], v[4:5] op_sel_hi:[1,0,1]
	global_store_dwordx4 v[136:137], v[132:135], off offset:512
	s_nop 1
	v_pk_fma_f32 v[134:135], v[164:165], s[2:3], v[2:3] op_sel_hi:[1,0,1]
	v_pk_fma_f32 v[132:133], v[162:163], s[2:3], v[0:1] op_sel_hi:[1,0,1]
	global_store_dwordx4 v[136:137], v[132:135], off offset:576
